# GEMM MFMA blocks: same-accumulator K-half pairs in snake order (neighbouring MFMAs share an operand register)
# speedup vs baseline: 1.0157x; 1.0077x over previous
; #define PG8_STAGE(bufoff, gbase, voff) do { _Pragma("unroll") for (int _i = 0; _i < 2; ++_i) \
;         __builtin_amdgcn_global_load_lds((const unsigned*)((const char*)(gbase) + (voff)[_i]), (PG8_LAS unsigned*)(lds + (bufoff) + ldsw + _i * 8192), 16, 0, 0); } while (0)
; #define PG8_LDA(dst, b, h) do { _Pragma("unroll") for (int m = 0; m < 4; ++m) _Pragma("unroll") for (int k = 0; k < 2; ++k) dst[m][k] = *(const PG8_LAS bf16x8*)(lds + PG8_SA(b, h) + aoff + m * 2048 + k * 1024); } while (0)
; #define PG8_LDB(dst, b, h) do { _Pragma("unroll") for (int n = 0; n < 2; ++n) _Pragma("unroll") for (int k = 0; k < 2; ++k) dst[n][k] = *(const PG8_LAS bf16x8*)(lds + PG8_SB(b, h) + boff + n * 2048 + k * 1024); } while (0)
; #define PG8_MMA(ai, bj, At, Bt) do { __builtin_amdgcn_s_setprio(1); _Pragma("unroll") for (int m = 0; m < 4; ++m) _Pragma("unroll") for (int n = 0; n < 2; ++n) _Pragma("unroll") for (int k = 0; k < 2; ++k) \
;         acc[ai][bj][m][n] = __builtin_amdgcn_mfma_f32_16x16x32_bf16(Bt[n][k], At[m][k], acc[ai][bj][m][n], 0, 0, 0); __builtin_amdgcn_s_setprio(0); } while (0)
; #define PG8_WAIT_V(n) asm volatile("s_waitcnt vmcnt(" #n ")" ::: "memory")
; #define PG8_WAIT_L(n) asm volatile("s_waitcnt lgkmcnt(" #n ")" ::: "memory")
; #define PG8_BAR __builtin_amdgcn_s_barrier()
; #define PG8_SCHED __builtin_amdgcn_sched_barrier(0)
;     ...
;             const bool last = (t == nt - 2);
;             const char* a1 = cA + (size_t)(t + 1) * kstep;
;             const char* a2 = last ? nA : cA + (size_t)(t + 2) * kstep; const char* b2 = last ? nB : cB + (size_t)(t + 2) * kstep;
;             const char* a3 = a2 + kstep; const char* b3 = b2 + kstep;
;             if (last && has_next) S.a_ready(nxt);
;             if constexpr (SP2) {
;             PG8_LDB(B0, 0, 0); PG8_LDB(B1, 0, 1); PG8_SCHED; PG8_LDA(At, 0, 0); PG8_STAGE(PG8_SA(1, 1), a1 + hstepA, voffA);
;             PG8_WAIT_V(8); PG8_WAIT_L(0); PG8_BAR; PG8_MMA(0, 0, At, B0); PG8_MMA(0, 1, At, B1); PG8_BAR; PG8_SCHED;
;             PG8_LDA(At, 0, 1); PG8_STAGE(PG8_SB(0, 0), b2, voffB); PG8_STAGE(PG8_SB(0, 1), b2 + hstep, voffB); PG8_STAGE(PG8_SA(0, 0), a2, voffA);
;             PG8_WAIT_V(8); PG8_WAIT_L(0); PG8_BAR; PG8_MMA(1, 0, At, B0); PG8_MMA(1, 1, At, B1); PG8_BAR; PG8_SCHED;
.LBB0_407:
	s_add_u32 s28, s30, 0xfff80080
	s_addc_u32 s29, s31, -1
	s_add_i32 s42, 0, 0x10000
	s_cmp_eq_u32 s93, 28
	s_cselect_b32 vcc_hi, s9, s29
	s_cselect_b32 vcc_lo, s25, s28
	v_add_u32_e32 v32, s42, v180
	s_cselect_b32 s29, s33, s50
	s_cselect_b32 s28, s40, s48
	s_add_i32 s46, 0, 0x14000
	ds_read_b128 v[136:139], v32
	ds_read_b128 v[140:143], v32 offset:1024
	ds_read_b128 v[144:147], v32 offset:2048
	ds_read_b128 v[148:151], v32 offset:3072
	v_add_u32_e32 v32, s46, v180
	ds_read_b128 v[166:169], v32
	ds_read_b128 v[170:173], v32 offset:1024
	ds_read_b128 v[174:177], v32 offset:2048
	ds_read_b128 v[198:201], v32 offset:3072
	v_lshl_add_u64 v[34:35], s[30:31], 0, v[162:163]
	s_add_i32 m0, s17, 0xc000
	ds_read_b128 v[202:205], v196
	ds_read_b128 v[206:209], v196 offset:1024
	ds_read_b128 v[210:213], v196 offset:2048
	ds_read_b128 v[214:217], v196 offset:3072
	ds_read_b128 v[218:221], v196 offset:4096
	ds_read_b128 v[222:225], v196 offset:5120
	ds_read_b128 v[226:229], v196 offset:6144
	ds_read_b128 v[240:243], v196 offset:7168
	global_load_lds_dwordx4 v[34:35], off
	v_lshl_add_u64 v[34:35], s[30:31], 0, v[164:165]
	s_add_i32 m0, s17, 0xe000
	s_nop 0
	global_load_lds_dwordx4 v[34:35], off
	s_waitcnt vmcnt(8)
	s_waitcnt lgkmcnt(0)
	s_barrier
	s_setprio 1
	s_waitcnt lgkmcnt(0)
	v_mfma_f32_16x16x32_bf16 v[132:135], v[136:139], v[202:205], v[132:135]
	v_mfma_f32_16x16x32_bf16 v[132:135], v[140:143], v[206:209], v[132:135]
	v_mfma_f32_16x16x32_bf16 v[128:131], v[148:151], v[206:209], v[128:131]
	v_mfma_f32_16x16x32_bf16 v[128:131], v[144:147], v[202:205], v[128:131]
	v_mfma_f32_16x16x32_bf16 v[112:115], v[144:147], v[210:213], v[112:115]
	v_mfma_f32_16x16x32_bf16 v[112:115], v[148:151], v[214:217], v[112:115]
	v_mfma_f32_16x16x32_bf16 v[116:119], v[140:143], v[214:217], v[116:119]
	v_mfma_f32_16x16x32_bf16 v[116:119], v[136:139], v[210:213], v[116:119]
	v_mfma_f32_16x16x32_bf16 v[100:103], v[136:139], v[218:221], v[100:103]
	v_mfma_f32_16x16x32_bf16 v[100:103], v[140:143], v[222:225], v[100:103]
	v_mfma_f32_16x16x32_bf16 v[96:99], v[148:151], v[222:225], v[96:99]
	v_mfma_f32_16x16x32_bf16 v[96:99], v[144:147], v[218:221], v[96:99]
	v_mfma_f32_16x16x32_bf16 v[80:83], v[144:147], v[226:229], v[80:83]
	v_mfma_f32_16x16x32_bf16 v[80:83], v[148:151], v[240:243], v[80:83]
	v_mfma_f32_16x16x32_bf16 v[84:87], v[140:143], v[240:243], v[84:87]
	v_mfma_f32_16x16x32_bf16 v[84:87], v[136:139], v[226:229], v[84:87]
	s_setprio 0
	s_setprio 1
	v_mfma_f32_16x16x32_bf16 v[124:127], v[166:169], v[202:205], v[124:127]
	v_mfma_f32_16x16x32_bf16 v[124:127], v[170:173], v[206:209], v[124:127]
	v_mfma_f32_16x16x32_bf16 v[120:123], v[198:201], v[206:209], v[120:123]
	v_mfma_f32_16x16x32_bf16 v[120:123], v[174:177], v[202:205], v[120:123]
	v_mfma_f32_16x16x32_bf16 v[104:107], v[174:177], v[210:213], v[104:107]
	v_mfma_f32_16x16x32_bf16 v[104:107], v[198:201], v[214:217], v[104:107]
	v_mfma_f32_16x16x32_bf16 v[108:111], v[170:173], v[214:217], v[108:111]
	v_mfma_f32_16x16x32_bf16 v[108:111], v[166:169], v[210:213], v[108:111]
	v_mfma_f32_16x16x32_bf16 v[92:95], v[166:169], v[218:221], v[92:95]
	v_mfma_f32_16x16x32_bf16 v[92:95], v[170:173], v[222:225], v[92:95]
	v_mfma_f32_16x16x32_bf16 v[88:91], v[198:201], v[222:225], v[88:91]
	v_mfma_f32_16x16x32_bf16 v[88:91], v[174:177], v[218:221], v[88:91]
	v_mfma_f32_16x16x32_bf16 v[72:75], v[174:177], v[226:229], v[72:75]
	v_mfma_f32_16x16x32_bf16 v[72:75], v[198:201], v[240:243], v[72:75]
	v_mfma_f32_16x16x32_bf16 v[76:79], v[170:173], v[240:243], v[76:79]
	v_mfma_f32_16x16x32_bf16 v[76:79], v[166:169], v[226:229], v[76:79]
	s_setprio 0
	s_barrier
	s_add_i32 s42, s42, s41
	v_lshl_add_u64 v[178:179], s[28:29], 0, v[154:155]
	s_mov_b32 m0, s42
	ds_read_b128 v[202:205], v196 offset:16384
	ds_read_b128 v[206:209], v196 offset:17408
	ds_read_b128 v[210:213], v196 offset:18432
	ds_read_b128 v[214:217], v196 offset:19456
	ds_read_b128 v[218:221], v196 offset:20480
	ds_read_b128 v[222:225], v196 offset:21504
	ds_read_b128 v[226:229], v196 offset:22528
	ds_read_b128 v[240:243], v196 offset:23552
	global_load_lds_dwordx4 v[178:179], off
	s_add_i32 m0, s42, 0x2000
	s_add_u32 s42, s28, 0x80000
	v_lshl_add_u64 v[186:187], s[28:29], 0, v[158:159]
	s_addc_u32 s43, s29, 0
	s_add_i32 s46, s46, s41
	global_load_lds_dwordx4 v[186:187], off
	v_lshl_add_u64 v[34:35], s[42:43], 0, v[154:155]
	s_mov_b32 m0, s46
	v_lshl_add_u64 v[188:189], vcc, 0, v[152:153]
	global_load_lds_dwordx4 v[34:35], off
	v_lshl_add_u64 v[34:35], s[42:43], 0, v[158:159]
	s_add_i32 m0, s46, 0x2000
	v_lshl_add_u64 v[190:191], vcc, 0, v[156:157]
	global_load_lds_dwordx4 v[34:35], off
	s_mov_b32 m0, s17
	s_nop 0
	global_load_lds_dwordx4 v[188:189], off
	s_mov_b32 m0, s53
	s_nop 0
	global_load_lds_dwordx4 v[190:191], off
	s_waitcnt vmcnt(8)
	s_waitcnt lgkmcnt(0)
	s_barrier
; #define PG8_STAGE(bufoff, gbase, voff) do { _Pragma("unroll") for (int _i = 0; _i < 2; ++_i) \
;         __builtin_amdgcn_global_load_lds((const unsigned*)((const char*)(gbase) + (voff)[_i]), (PG8_LAS unsigned*)(lds + (bufoff) + ldsw + _i * 8192), 16, 0, 0); } while (0)
; #define PG8_LDA(dst, b, h) do { _Pragma("unroll") for (int m = 0; m < 4; ++m) _Pragma("unroll") for (int k = 0; k < 2; ++k) dst[m][k] = *(const PG8_LAS bf16x8*)(lds + PG8_SA(b, h) + aoff + m * 2048 + k * 1024); } while (0)
; #define PG8_LDB(dst, b, h) do { _Pragma("unroll") for (int n = 0; n < 2; ++n) _Pragma("unroll") for (int k = 0; k < 2; ++k) dst[n][k] = *(const PG8_LAS bf16x8*)(lds + PG8_SB(b, h) + boff + n * 2048 + k * 1024); } while (0)
; #define PG8_MMA(ai, bj, At, Bt) do { __builtin_amdgcn_s_setprio(1); _Pragma("unroll") for (int m = 0; m < 4; ++m) _Pragma("unroll") for (int n = 0; n < 2; ++n) _Pragma("unroll") for (int k = 0; k < 2; ++k) \
;         acc[ai][bj][m][n] = __builtin_amdgcn_mfma_f32_16x16x32_bf16(Bt[n][k], At[m][k], acc[ai][bj][m][n], 0, 0, 0); __builtin_amdgcn_s_setprio(0); } while (0)
; #define PG8_WAIT_V(n) asm volatile("s_waitcnt vmcnt(" #n ")" ::: "memory")
; #define PG8_WAIT_L(n) asm volatile("s_waitcnt lgkmcnt(" #n ")" ::: "memory")
; #define PG8_BAR __builtin_amdgcn_s_barrier()
; #define PG8_SCHED __builtin_amdgcn_sched_barrier(0)
;     ...
;             PG8_WAIT_V(8); PG8_WAIT_L(0); PG8_BAR; PG8_MMA(1, 0, At, B0); PG8_MMA(1, 1, At, B1); PG8_BAR; PG8_SCHED;
;             PG8_LDB(B0, 1, 0); PG8_LDB(B1, 1, 1); PG8_SCHED; PG8_LDA(At, 1, 0); PG8_STAGE(PG8_SA(0, 1), a2 + hstepA, voffA);
;             PG8_WAIT_V(8); PG8_WAIT_L(0); PG8_BAR; PG8_MMA(0, 0, At, B0); PG8_MMA(0, 1, At, B1); PG8_BAR; PG8_SCHED;
	s_setprio 1
	s_waitcnt lgkmcnt(0)
	v_mfma_f32_16x16x32_bf16 v[68:71], v[136:139], v[202:205], v[68:71]
	v_mfma_f32_16x16x32_bf16 v[68:71], v[140:143], v[206:209], v[68:71]
	v_mfma_f32_16x16x32_bf16 v[64:67], v[148:151], v[206:209], v[64:67]
	v_mfma_f32_16x16x32_bf16 v[64:67], v[144:147], v[202:205], v[64:67]
	v_mfma_f32_16x16x32_bf16 v[48:51], v[144:147], v[210:213], v[48:51]
	v_mfma_f32_16x16x32_bf16 v[48:51], v[148:151], v[214:217], v[48:51]
	v_mfma_f32_16x16x32_bf16 v[52:55], v[140:143], v[214:217], v[52:55]
	v_mfma_f32_16x16x32_bf16 v[52:55], v[136:139], v[210:213], v[52:55]
	v_mfma_f32_16x16x32_bf16 v[34:37], v[136:139], v[218:221], v[36:39]
	v_mfma_f32_16x16x32_bf16 v[34:37], v[140:143], v[222:225], v[34:37]
	v_mfma_f32_16x16x32_bf16 v[26:29], v[148:151], v[222:225], v[26:29]
	v_mfma_f32_16x16x32_bf16 v[26:29], v[144:147], v[218:221], v[26:29]
	v_mfma_f32_16x16x32_bf16 v[10:13], v[144:147], v[226:229], v[10:13]
	v_mfma_f32_16x16x32_bf16 v[10:13], v[148:151], v[240:243], v[10:13]
	v_mfma_f32_16x16x32_bf16 v[14:17], v[140:143], v[240:243], v[14:17]
	v_mfma_f32_16x16x32_bf16 v[14:17], v[136:139], v[226:229], v[14:17]
	s_setprio 0
	s_setprio 1
	v_mfma_f32_16x16x32_bf16 v[60:63], v[166:169], v[202:205], v[60:63]
	v_mfma_f32_16x16x32_bf16 v[60:63], v[170:173], v[206:209], v[60:63]
	v_mfma_f32_16x16x32_bf16 v[56:59], v[198:201], v[206:209], v[56:59]
	v_mfma_f32_16x16x32_bf16 v[56:59], v[174:177], v[202:205], v[56:59]
	v_mfma_f32_16x16x32_bf16 v[38:41], v[174:177], v[210:213], v[40:43]
	v_mfma_f32_16x16x32_bf16 v[40:43], v[198:201], v[214:217], v[38:41]
	v_mfma_f32_16x16x32_bf16 v[44:47], v[170:173], v[214:217], v[44:47]
	v_mfma_f32_16x16x32_bf16 v[44:47], v[166:169], v[210:213], v[44:47]
	v_mfma_f32_16x16x32_bf16 v[22:25], v[166:169], v[218:221], v[22:25]
	v_mfma_f32_16x16x32_bf16 v[22:25], v[170:173], v[222:225], v[22:25]
	v_mfma_f32_16x16x32_bf16 v[18:21], v[198:201], v[222:225], v[18:21]
	v_mfma_f32_16x16x32_bf16 v[18:21], v[174:177], v[218:221], v[18:21]
	v_mfma_f32_16x16x32_bf16 v[2:5], v[174:177], v[226:229], v[2:5]
	v_mfma_f32_16x16x32_bf16 v[2:5], v[198:201], v[240:243], v[2:5]
	v_mfma_f32_16x16x32_bf16 v[6:9], v[170:173], v[240:243], v[6:9]
	v_mfma_f32_16x16x32_bf16 v[6:9], v[166:169], v[226:229], v[6:9]
	s_setprio 0
	s_barrier
	s_add_i32 s46, 0, 0x18000
	v_add_u32_e32 v32, s46, v180
	s_add_i32 s47, 0, 0x1c000
	ds_read_b128 v[136:139], v32
	ds_read_b128 v[140:143], v32 offset:1024
	ds_read_b128 v[144:147], v32 offset:2048
	ds_read_b128 v[148:151], v32 offset:3072
	v_add_u32_e32 v32, s47, v180
	ds_read_b128 v[166:169], v32
	ds_read_b128 v[170:173], v32 offset:1024
	ds_read_b128 v[174:177], v32 offset:2048
	ds_read_b128 v[198:201], v32 offset:3072
	s_add_u32 s42, vcc_lo, 0x80000
	s_addc_u32 s43, vcc_hi, 0
	s_mov_b32 m0, s74
	v_lshl_add_u64 v[38:39], s[42:43], 0, v[152:153]
	ds_read_b128 v[202:205], v196 offset:32768
	ds_read_b128 v[206:209], v196 offset:33792
	ds_read_b128 v[210:213], v196 offset:34816
	ds_read_b128 v[214:217], v196 offset:35840
	ds_read_b128 v[218:221], v196 offset:36864
	ds_read_b128 v[222:225], v196 offset:37888
	ds_read_b128 v[226:229], v196 offset:38912
	ds_read_b128 v[240:243], v196 offset:39936
	global_load_lds_dwordx4 v[38:39], off
	v_lshl_add_u64 v[38:39], s[42:43], 0, v[156:157]
	s_mov_b32 m0, s78
	s_nop 0
	global_load_lds_dwordx4 v[38:39], off
	s_waitcnt vmcnt(8)
	s_waitcnt lgkmcnt(0)
	s_barrier
	s_setprio 1
	s_waitcnt lgkmcnt(0)
	v_mfma_f32_16x16x32_bf16 v[132:135], v[136:139], v[202:205], v[132:135]
	v_mfma_f32_16x16x32_bf16 v[132:135], v[140:143], v[206:209], v[132:135]
	v_mfma_f32_16x16x32_bf16 v[128:131], v[148:151], v[206:209], v[128:131]
	v_mfma_f32_16x16x32_bf16 v[128:131], v[144:147], v[202:205], v[128:131]
	v_mfma_f32_16x16x32_bf16 v[112:115], v[144:147], v[210:213], v[112:115]
	v_mfma_f32_16x16x32_bf16 v[112:115], v[148:151], v[214:217], v[112:115]
	v_mfma_f32_16x16x32_bf16 v[116:119], v[140:143], v[214:217], v[116:119]
	v_mfma_f32_16x16x32_bf16 v[116:119], v[136:139], v[210:213], v[116:119]
	v_mfma_f32_16x16x32_bf16 v[100:103], v[136:139], v[218:221], v[100:103]
	v_mfma_f32_16x16x32_bf16 v[100:103], v[140:143], v[222:225], v[100:103]
	v_mfma_f32_16x16x32_bf16 v[96:99], v[148:151], v[222:225], v[96:99]
	v_mfma_f32_16x16x32_bf16 v[96:99], v[144:147], v[218:221], v[96:99]
	v_mfma_f32_16x16x32_bf16 v[80:83], v[144:147], v[226:229], v[80:83]
	v_mfma_f32_16x16x32_bf16 v[80:83], v[148:151], v[240:243], v[80:83]
	v_mfma_f32_16x16x32_bf16 v[84:87], v[140:143], v[240:243], v[84:87]
	v_mfma_f32_16x16x32_bf16 v[84:87], v[136:139], v[226:229], v[84:87]
	s_setprio 0
	s_setprio 1
	v_mfma_f32_16x16x32_bf16 v[124:127], v[166:169], v[202:205], v[124:127]
	v_mfma_f32_16x16x32_bf16 v[124:127], v[170:173], v[206:209], v[124:127]
	v_mfma_f32_16x16x32_bf16 v[120:123], v[198:201], v[206:209], v[120:123]
	v_mfma_f32_16x16x32_bf16 v[120:123], v[174:177], v[202:205], v[120:123]
	v_mfma_f32_16x16x32_bf16 v[104:107], v[174:177], v[210:213], v[104:107]
	v_mfma_f32_16x16x32_bf16 v[104:107], v[198:201], v[214:217], v[104:107]
	v_mfma_f32_16x16x32_bf16 v[108:111], v[170:173], v[214:217], v[108:111]
	v_mfma_f32_16x16x32_bf16 v[108:111], v[166:169], v[210:213], v[108:111]
	v_mfma_f32_16x16x32_bf16 v[92:95], v[166:169], v[218:221], v[92:95]
	v_mfma_f32_16x16x32_bf16 v[92:95], v[170:173], v[222:225], v[92:95]
	v_mfma_f32_16x16x32_bf16 v[88:91], v[198:201], v[222:225], v[88:91]
	v_mfma_f32_16x16x32_bf16 v[88:91], v[174:177], v[218:221], v[88:91]
	v_mfma_f32_16x16x32_bf16 v[72:75], v[174:177], v[226:229], v[72:75]
	v_mfma_f32_16x16x32_bf16 v[72:75], v[198:201], v[240:243], v[72:75]
	v_mfma_f32_16x16x32_bf16 v[76:79], v[170:173], v[240:243], v[76:79]
	v_mfma_f32_16x16x32_bf16 v[76:79], v[166:169], v[226:229], v[76:79]
	s_setprio 0
	s_barrier
; #define PG8_STAGE(bufoff, gbase, voff) do { _Pragma("unroll") for (int _i = 0; _i < 2; ++_i) \
;         __builtin_amdgcn_global_load_lds((const unsigned*)((const char*)(gbase) + (voff)[_i]), (PG8_LAS unsigned*)(lds + (bufoff) + ldsw + _i * 8192), 16, 0, 0); } while (0)
; #define PG8_LDA(dst, b, h) do { _Pragma("unroll") for (int m = 0; m < 4; ++m) _Pragma("unroll") for (int k = 0; k < 2; ++k) dst[m][k] = *(const PG8_LAS bf16x8*)(lds + PG8_SA(b, h) + aoff + m * 2048 + k * 1024); } while (0)
; #define PG8_MMA(ai, bj, At, Bt) do { __builtin_amdgcn_s_setprio(1); _Pragma("unroll") for (int m = 0; m < 4; ++m) _Pragma("unroll") for (int n = 0; n < 2; ++n) _Pragma("unroll") for (int k = 0; k < 2; ++k) \
;         acc[ai][bj][m][n] = __builtin_amdgcn_mfma_f32_16x16x32_bf16(Bt[n][k], At[m][k], acc[ai][bj][m][n], 0, 0, 0); __builtin_amdgcn_s_setprio(0); } while (0)
; #define PG8_WAIT_V(n) asm volatile("s_waitcnt vmcnt(" #n ")" ::: "memory")
; #define PG8_WAIT_L(n) asm volatile("s_waitcnt lgkmcnt(" #n ")" ::: "memory")
; #define PG8_BAR __builtin_amdgcn_s_barrier()
; #define PG8_SCHED __builtin_amdgcn_sched_barrier(0)
;     ...
;             PG8_LDA(At, 1, 1); PG8_STAGE(PG8_SB(1, 0), b3, voffB); PG8_STAGE(PG8_SB(1, 1), b3 + hstep, voffB); PG8_STAGE(PG8_SA(1, 0), a3, voffA);
;             PG8_WAIT_V(8); PG8_WAIT_L(0); PG8_BAR; PG8_MMA(1, 0, At, B0); PG8_MMA(1, 1, At, B1); PG8_BAR; PG8_SCHED;
;     ...
;         if constexpr (ALIGN_EPI) { if (wr == 0) PG8_BAR; }
	s_add_i32 s42, s46, s41
	v_lshl_add_u64 v[38:39], v[178:179], 0, s[64:65]
	s_mov_b32 m0, s42
	ds_read_b128 v[202:205], v196 offset:49152
	ds_read_b128 v[206:209], v196 offset:50176
	ds_read_b128 v[210:213], v196 offset:51200
	ds_read_b128 v[214:217], v196 offset:52224
	ds_read_b128 v[218:221], v196 offset:53248
	ds_read_b128 v[222:225], v196 offset:54272
	ds_read_b128 v[226:229], v196 offset:55296
	ds_read_b128 v[240:243], v196 offset:56320
	global_load_lds_dwordx4 v[38:39], off
	s_add_i32 m0, s42, 0x2000
	s_add_u32 s28, s28, 0x80080
	v_lshl_add_u64 v[38:39], v[186:187], 0, s[64:65]
	s_addc_u32 s29, s29, 0
	s_add_i32 s42, s47, s41
	global_load_lds_dwordx4 v[38:39], off
	v_lshl_add_u64 v[38:39], s[28:29], 0, v[154:155]
	s_mov_b32 m0, s42
	s_nop 0
	global_load_lds_dwordx4 v[38:39], off
	v_lshl_add_u64 v[38:39], s[28:29], 0, v[158:159]
	s_add_i32 m0, s42, 0x2000
	s_nop 0
	global_load_lds_dwordx4 v[38:39], off
	v_lshl_add_u64 v[38:39], v[188:189], 0, s[64:65]
	s_mov_b32 m0, s79
	s_nop 0
	global_load_lds_dwordx4 v[38:39], off
	v_lshl_add_u64 v[38:39], v[190:191], 0, s[64:65]
	s_mov_b32 m0, s4
	s_nop 0
	global_load_lds_dwordx4 v[38:39], off
	s_waitcnt vmcnt(8)
	s_waitcnt lgkmcnt(0)
	s_barrier
	s_setprio 1
	s_waitcnt lgkmcnt(0)
	v_mfma_f32_16x16x32_bf16 v[68:71], v[136:139], v[202:205], v[68:71]
	v_mfma_f32_16x16x32_bf16 v[68:71], v[140:143], v[206:209], v[68:71]
	v_mfma_f32_16x16x32_bf16 v[64:67], v[148:151], v[206:209], v[64:67]
	v_mfma_f32_16x16x32_bf16 v[64:67], v[144:147], v[202:205], v[64:67]
	v_mfma_f32_16x16x32_bf16 v[48:51], v[144:147], v[210:213], v[48:51]
	v_mfma_f32_16x16x32_bf16 v[48:51], v[148:151], v[214:217], v[48:51]
	v_mfma_f32_16x16x32_bf16 v[52:55], v[140:143], v[214:217], v[52:55]
	v_mfma_f32_16x16x32_bf16 v[52:55], v[136:139], v[210:213], v[52:55]
	v_mfma_f32_16x16x32_bf16 v[34:37], v[136:139], v[218:221], v[34:37]
	v_mfma_f32_16x16x32_bf16 v[36:39], v[140:143], v[222:225], v[34:37]
	v_mfma_f32_16x16x32_bf16 v[26:29], v[148:151], v[222:225], v[26:29]
	v_mfma_f32_16x16x32_bf16 v[26:29], v[144:147], v[218:221], v[26:29]
	v_mfma_f32_16x16x32_bf16 v[10:13], v[144:147], v[226:229], v[10:13]
	v_mfma_f32_16x16x32_bf16 v[10:13], v[148:151], v[240:243], v[10:13]
	v_mfma_f32_16x16x32_bf16 v[14:17], v[140:143], v[240:243], v[14:17]
	v_mfma_f32_16x16x32_bf16 v[14:17], v[136:139], v[226:229], v[14:17]
	s_setprio 0
	s_setprio 1
	v_mfma_f32_16x16x32_bf16 v[60:63], v[166:169], v[202:205], v[60:63]
	v_mfma_f32_16x16x32_bf16 v[60:63], v[170:173], v[206:209], v[60:63]
	v_mfma_f32_16x16x32_bf16 v[56:59], v[198:201], v[206:209], v[56:59]
	v_mfma_f32_16x16x32_bf16 v[56:59], v[174:177], v[202:205], v[56:59]
	v_mfma_f32_16x16x32_bf16 v[40:43], v[174:177], v[210:213], v[40:43]
	v_mfma_f32_16x16x32_bf16 v[40:43], v[198:201], v[214:217], v[40:43]
	v_mfma_f32_16x16x32_bf16 v[44:47], v[170:173], v[214:217], v[44:47]
	v_mfma_f32_16x16x32_bf16 v[44:47], v[166:169], v[210:213], v[44:47]
	v_mfma_f32_16x16x32_bf16 v[22:25], v[166:169], v[218:221], v[22:25]
	v_mfma_f32_16x16x32_bf16 v[22:25], v[170:173], v[222:225], v[22:25]
	v_mfma_f32_16x16x32_bf16 v[18:21], v[198:201], v[222:225], v[18:21]
	v_mfma_f32_16x16x32_bf16 v[18:21], v[174:177], v[218:221], v[18:21]
	v_mfma_f32_16x16x32_bf16 v[2:5], v[174:177], v[226:229], v[2:5]
	v_mfma_f32_16x16x32_bf16 v[2:5], v[198:201], v[240:243], v[2:5]
	v_mfma_f32_16x16x32_bf16 v[6:9], v[170:173], v[240:243], v[6:9]
	v_mfma_f32_16x16x32_bf16 v[6:9], v[166:169], v[226:229], v[6:9]
	s_setprio 0
	s_barrier
	s_add_i32 s93, s93, 2
	s_add_u32 s30, s30, 0x100
	s_addc_u32 s31, s31, 0
	s_add_u32 s48, s48, 0x100
	s_addc_u32 s50, s50, 0
	s_cmp_gt_u32 s93, 29
	s_cbranch_scc0 .LBB0_407
	s_and_b64 vcc, exec, s[60:61]
	s_cbranch_vccz .LBB0_410
	s_barrier

; #define PG8_STAGE(bufoff, gbase, voff) do { _Pragma("unroll") for (int _i = 0; _i < 2; ++_i) \
;         __builtin_amdgcn_global_load_lds((const unsigned*)((const char*)(gbase) + (voff)[_i]), (PG8_LAS unsigned*)(lds + (bufoff) + ldsw + _i * 8192), 16, 0, 0); } while (0)
; #define PG8_LDA(dst, b, h) do { _Pragma("unroll") for (int m = 0; m < 4; ++m) _Pragma("unroll") for (int k = 0; k < 2; ++k) dst[m][k] = *(const PG8_LAS bf16x8*)(lds + PG8_SA(b, h) + aoff + m * 2048 + k * 1024); } while (0)
; #define PG8_LDB(dst, b, h) do { _Pragma("unroll") for (int n = 0; n < 2; ++n) _Pragma("unroll") for (int k = 0; k < 2; ++k) dst[n][k] = *(const PG8_LAS bf16x8*)(lds + PG8_SB(b, h) + boff + n * 2048 + k * 1024); } while (0)
; #define PG8_MMA(ai, bj, At, Bt) do { __builtin_amdgcn_s_setprio(1); _Pragma("unroll") for (int m = 0; m < 4; ++m) _Pragma("unroll") for (int n = 0; n < 2; ++n) _Pragma("unroll") for (int k = 0; k < 2; ++k) \
;         acc[ai][bj][m][n] = __builtin_amdgcn_mfma_f32_16x16x32_bf16(Bt[n][k], At[m][k], acc[ai][bj][m][n], 0, 0, 0); __builtin_amdgcn_s_setprio(0); } while (0)
; #define PG8_WAIT_V(n) asm volatile("s_waitcnt vmcnt(" #n ")" ::: "memory")
; #define PG8_WAIT_L(n) asm volatile("s_waitcnt lgkmcnt(" #n ")" ::: "memory")
; #define PG8_BAR __builtin_amdgcn_s_barrier()
; #define PG8_SCHED __builtin_amdgcn_sched_barrier(0)
;     ...
;             const bool last = (t == nt - 2);
;             const char* a1 = cA + (size_t)(t + 1) * kstep;
;             const char* a2 = last ? nA : cA + (size_t)(t + 2) * kstep; const char* b2 = last ? nB : cB + (size_t)(t + 2) * kstep;
;             const char* a3 = a2 + kstep; const char* b3 = b2 + kstep;
;             if (last && has_next) S.a_ready(nxt);
;             if constexpr (SP2) {
;             PG8_LDB(B0, 0, 0); PG8_LDB(B1, 0, 1); PG8_SCHED; PG8_LDA(At, 0, 0); PG8_STAGE(PG8_SA(1, 1), a1 + hstepA, voffA);
;             PG8_WAIT_V(8); PG8_WAIT_L(0); PG8_BAR; PG8_MMA(0, 0, At, B0); PG8_MMA(0, 1, At, B1); PG8_BAR; PG8_SCHED;
;             PG8_LDA(At, 0, 1); PG8_STAGE(PG8_SB(0, 0), b2, voffB); PG8_STAGE(PG8_SB(0, 1), b2 + hstep, voffB); PG8_STAGE(PG8_SA(0, 0), a2, voffA);
;             PG8_WAIT_V(8); PG8_WAIT_L(0); PG8_BAR; PG8_MMA(1, 0, At, B0); PG8_MMA(1, 1, At, B1); PG8_BAR; PG8_SCHED;
.LBB0_748:
	s_add_u32 s4, s18, 0x100
	s_addc_u32 s5, s19, 0
	s_add_i32 s42, 0, 0x10000
	s_cmp_eq_u32 s78, 4
	s_cselect_b32 s27, s13, s5
	s_cselect_b32 s26, s12, s4
	v_add_u32_e32 v153, s42, v150
	s_cselect_b32 s25, s11, s74
	s_cselect_b32 s24, s33, s48
	s_add_i32 s43, 0, 0x14000
	ds_read_b128 v[142:145], v153
	ds_read_b128 v[146:149], v153 offset:1024
	ds_read_b128 v[154:157], v153 offset:2048
	ds_read_b128 v[158:161], v153 offset:3072
	v_add_u32_e32 v153, s43, v150
	ds_read_b128 v[162:165], v153
	ds_read_b128 v[166:169], v153 offset:1024
	ds_read_b128 v[170:173], v153 offset:2048
	ds_read_b128 v[174:177], v153 offset:3072
	v_lshl_add_u64 v[182:183], s[18:19], 0, v[138:139]
	s_add_i32 m0, s17, 0xc000
	ds_read_b128 v[178:181], v152
	ds_read_b128 v[196:199], v152 offset:1024
	ds_read_b128 v[200:203], v152 offset:2048
	ds_read_b128 v[204:207], v152 offset:3072
	ds_read_b128 v[208:211], v152 offset:4096
	ds_read_b128 v[212:215], v152 offset:5120
	ds_read_b128 v[216:219], v152 offset:6144
	ds_read_b128 v[220:223], v152 offset:7168
	global_load_lds_dwordx4 v[182:183], off
	v_lshl_add_u64 v[182:183], s[18:19], 0, v[140:141]
	s_add_i32 m0, s17, 0xe000
	s_nop 0
	global_load_lds_dwordx4 v[182:183], off
	s_waitcnt vmcnt(8)
	s_waitcnt lgkmcnt(0)
	s_barrier
	s_setprio 1
	s_waitcnt lgkmcnt(0)
	v_mfma_f32_16x16x32_bf16 v[130:133], v[142:145], v[178:181], v[130:133]
	v_mfma_f32_16x16x32_bf16 v[130:133], v[146:149], v[196:199], v[130:133]
	v_mfma_f32_16x16x32_bf16 v[126:129], v[158:161], v[196:199], v[126:129]
	v_mfma_f32_16x16x32_bf16 v[126:129], v[154:157], v[178:181], v[126:129]
	v_mfma_f32_16x16x32_bf16 v[110:113], v[154:157], v[200:203], v[110:113]
	v_mfma_f32_16x16x32_bf16 v[110:113], v[158:161], v[204:207], v[110:113]
	v_mfma_f32_16x16x32_bf16 v[114:117], v[146:149], v[204:207], v[114:117]
	v_mfma_f32_16x16x32_bf16 v[114:117], v[142:145], v[200:203], v[114:117]
	v_mfma_f32_16x16x32_bf16 v[98:101], v[142:145], v[208:211], v[98:101]
	v_mfma_f32_16x16x32_bf16 v[98:101], v[146:149], v[212:215], v[98:101]
	v_mfma_f32_16x16x32_bf16 v[94:97], v[158:161], v[212:215], v[94:97]
	v_mfma_f32_16x16x32_bf16 v[94:97], v[154:157], v[208:211], v[94:97]
	v_mfma_f32_16x16x32_bf16 v[78:81], v[154:157], v[216:219], v[78:81]
	v_mfma_f32_16x16x32_bf16 v[78:81], v[158:161], v[220:223], v[78:81]
	v_mfma_f32_16x16x32_bf16 v[82:85], v[146:149], v[220:223], v[82:85]
	v_mfma_f32_16x16x32_bf16 v[82:85], v[142:145], v[216:219], v[82:85]
	s_setprio 0
	s_setprio 1
	v_mfma_f32_16x16x32_bf16 v[122:125], v[162:165], v[178:181], v[122:125]
	v_mfma_f32_16x16x32_bf16 v[122:125], v[166:169], v[196:199], v[122:125]
	v_mfma_f32_16x16x32_bf16 v[118:121], v[174:177], v[196:199], v[118:121]
	v_mfma_f32_16x16x32_bf16 v[118:121], v[170:173], v[178:181], v[118:121]
	v_mfma_f32_16x16x32_bf16 v[102:105], v[170:173], v[200:203], v[102:105]
	v_mfma_f32_16x16x32_bf16 v[102:105], v[174:177], v[204:207], v[102:105]
	v_mfma_f32_16x16x32_bf16 v[106:109], v[166:169], v[204:207], v[106:109]
	v_mfma_f32_16x16x32_bf16 v[106:109], v[162:165], v[200:203], v[106:109]
	v_mfma_f32_16x16x32_bf16 v[90:93], v[162:165], v[208:211], v[90:93]
	v_mfma_f32_16x16x32_bf16 v[90:93], v[166:169], v[212:215], v[90:93]
	v_mfma_f32_16x16x32_bf16 v[86:89], v[174:177], v[212:215], v[86:89]
	v_mfma_f32_16x16x32_bf16 v[86:89], v[170:173], v[208:211], v[86:89]
	v_mfma_f32_16x16x32_bf16 v[70:73], v[170:173], v[216:219], v[70:73]
	v_mfma_f32_16x16x32_bf16 v[70:73], v[174:177], v[220:223], v[70:73]
	v_mfma_f32_16x16x32_bf16 v[74:77], v[166:169], v[220:223], v[74:77]
	v_mfma_f32_16x16x32_bf16 v[74:77], v[162:165], v[216:219], v[74:77]
	s_setprio 0
	s_barrier
	s_add_i32 s18, s42, s30
	v_lshl_add_u64 v[182:183], s[24:25], 0, v[32:33]
	s_mov_b32 m0, s18
	ds_read_b128 v[178:181], v152 offset:16384
	ds_read_b128 v[196:199], v152 offset:17408
	ds_read_b128 v[200:203], v152 offset:18432
	ds_read_b128 v[204:207], v152 offset:19456
	ds_read_b128 v[208:211], v152 offset:20480
	ds_read_b128 v[212:215], v152 offset:21504
	ds_read_b128 v[216:219], v152 offset:22528
	ds_read_b128 v[220:223], v152 offset:23552
	global_load_lds_dwordx4 v[182:183], off
	s_add_i32 m0, s18, 0x2000
	s_add_u32 s18, s24, 0x20000
	v_lshl_add_u64 v[186:187], s[24:25], 0, v[136:137]
	s_addc_u32 s19, s25, 0
	s_add_i32 s42, s43, s30
	global_load_lds_dwordx4 v[186:187], off
	v_lshl_add_u64 v[188:189], s[18:19], 0, v[32:33]
	s_mov_b32 m0, s42
	v_lshl_add_u64 v[190:191], s[26:27], 0, v[134:135]
	global_load_lds_dwordx4 v[188:189], off
	v_lshl_add_u64 v[188:189], s[18:19], 0, v[136:137]
	s_add_i32 m0, s42, 0x2000
	s_nop 0
	global_load_lds_dwordx4 v[188:189], off
	v_lshl_add_u64 v[188:189], s[26:27], 0, v[30:31]
	s_mov_b32 m0, s17
	s_nop 0
	global_load_lds_dwordx4 v[188:189], off
	s_mov_b32 m0, s31
	s_nop 0
	global_load_lds_dwordx4 v[190:191], off
	s_waitcnt vmcnt(8)
	s_waitcnt lgkmcnt(0)
	s_barrier
; #define PG8_STAGE(bufoff, gbase, voff) do { _Pragma("unroll") for (int _i = 0; _i < 2; ++_i) \
;         __builtin_amdgcn_global_load_lds((const unsigned*)((const char*)(gbase) + (voff)[_i]), (PG8_LAS unsigned*)(lds + (bufoff) + ldsw + _i * 8192), 16, 0, 0); } while (0)
; #define PG8_LDA(dst, b, h) do { _Pragma("unroll") for (int m = 0; m < 4; ++m) _Pragma("unroll") for (int k = 0; k < 2; ++k) dst[m][k] = *(const PG8_LAS bf16x8*)(lds + PG8_SA(b, h) + aoff + m * 2048 + k * 1024); } while (0)
; #define PG8_LDB(dst, b, h) do { _Pragma("unroll") for (int n = 0; n < 2; ++n) _Pragma("unroll") for (int k = 0; k < 2; ++k) dst[n][k] = *(const PG8_LAS bf16x8*)(lds + PG8_SB(b, h) + boff + n * 2048 + k * 1024); } while (0)
; #define PG8_MMA(ai, bj, At, Bt) do { __builtin_amdgcn_s_setprio(1); _Pragma("unroll") for (int m = 0; m < 4; ++m) _Pragma("unroll") for (int n = 0; n < 2; ++n) _Pragma("unroll") for (int k = 0; k < 2; ++k) \
;         acc[ai][bj][m][n] = __builtin_amdgcn_mfma_f32_16x16x32_bf16(Bt[n][k], At[m][k], acc[ai][bj][m][n], 0, 0, 0); __builtin_amdgcn_s_setprio(0); } while (0)
; #define PG8_WAIT_V(n) asm volatile("s_waitcnt vmcnt(" #n ")" ::: "memory")
; #define PG8_WAIT_L(n) asm volatile("s_waitcnt lgkmcnt(" #n ")" ::: "memory")
; #define PG8_BAR __builtin_amdgcn_s_barrier()
; #define PG8_SCHED __builtin_amdgcn_sched_barrier(0)
;     ...
;             PG8_WAIT_V(8); PG8_WAIT_L(0); PG8_BAR; PG8_MMA(1, 0, At, B0); PG8_MMA(1, 1, At, B1); PG8_BAR; PG8_SCHED;
;             PG8_LDB(B0, 1, 0); PG8_LDB(B1, 1, 1); PG8_SCHED; PG8_LDA(At, 1, 0); PG8_STAGE(PG8_SA(0, 1), a2 + hstepA, voffA);
;             PG8_WAIT_V(8); PG8_WAIT_L(0); PG8_BAR; PG8_MMA(0, 0, At, B0); PG8_MMA(0, 1, At, B1); PG8_BAR; PG8_SCHED;
	s_setprio 1
	s_waitcnt lgkmcnt(0)
	v_mfma_f32_16x16x32_bf16 v[66:69], v[142:145], v[178:181], v[66:69]
	v_mfma_f32_16x16x32_bf16 v[66:69], v[146:149], v[196:199], v[66:69]
	v_mfma_f32_16x16x32_bf16 v[62:65], v[158:161], v[196:199], v[62:65]
	v_mfma_f32_16x16x32_bf16 v[62:65], v[154:157], v[178:181], v[62:65]
	v_mfma_f32_16x16x32_bf16 v[46:49], v[154:157], v[200:203], v[46:49]
	v_mfma_f32_16x16x32_bf16 v[46:49], v[158:161], v[204:207], v[46:49]
	v_mfma_f32_16x16x32_bf16 v[50:53], v[146:149], v[204:207], v[50:53]
	v_mfma_f32_16x16x32_bf16 v[50:53], v[142:145], v[200:203], v[50:53]
	v_mfma_f32_16x16x32_bf16 v[34:37], v[142:145], v[208:211], v[34:37]
	v_mfma_f32_16x16x32_bf16 v[34:37], v[146:149], v[212:215], v[34:37]
	v_mfma_f32_16x16x32_bf16 v[26:29], v[158:161], v[212:215], v[26:29]
	v_mfma_f32_16x16x32_bf16 v[26:29], v[154:157], v[208:211], v[26:29]
	v_mfma_f32_16x16x32_bf16 v[10:13], v[154:157], v[216:219], v[10:13]
	v_mfma_f32_16x16x32_bf16 v[10:13], v[158:161], v[220:223], v[10:13]
	v_mfma_f32_16x16x32_bf16 v[14:17], v[146:149], v[220:223], v[14:17]
	v_mfma_f32_16x16x32_bf16 v[14:17], v[142:145], v[216:219], v[14:17]
	s_setprio 0
	s_setprio 1
	v_mfma_f32_16x16x32_bf16 v[58:61], v[162:165], v[178:181], v[58:61]
	v_mfma_f32_16x16x32_bf16 v[58:61], v[166:169], v[196:199], v[58:61]
	v_mfma_f32_16x16x32_bf16 v[54:57], v[174:177], v[196:199], v[54:57]
	v_mfma_f32_16x16x32_bf16 v[54:57], v[170:173], v[178:181], v[54:57]
	v_mfma_f32_16x16x32_bf16 v[38:41], v[170:173], v[200:203], v[38:41]
	v_mfma_f32_16x16x32_bf16 v[38:41], v[174:177], v[204:207], v[38:41]
	v_mfma_f32_16x16x32_bf16 v[42:45], v[166:169], v[204:207], v[42:45]
	v_mfma_f32_16x16x32_bf16 v[42:45], v[162:165], v[200:203], v[42:45]
	v_mfma_f32_16x16x32_bf16 v[22:25], v[162:165], v[208:211], v[22:25]
	v_mfma_f32_16x16x32_bf16 v[22:25], v[166:169], v[212:215], v[22:25]
	v_mfma_f32_16x16x32_bf16 v[18:21], v[174:177], v[212:215], v[18:21]
	v_mfma_f32_16x16x32_bf16 v[18:21], v[170:173], v[208:211], v[18:21]
	v_mfma_f32_16x16x32_bf16 v[2:5], v[170:173], v[216:219], v[2:5]
	v_mfma_f32_16x16x32_bf16 v[2:5], v[174:177], v[220:223], v[2:5]
	v_mfma_f32_16x16x32_bf16 v[6:9], v[166:169], v[220:223], v[6:9]
	v_mfma_f32_16x16x32_bf16 v[6:9], v[162:165], v[216:219], v[6:9]
	s_setprio 0
	s_barrier
	s_add_i32 s42, 0, 0x18000
	v_add_u32_e32 v153, s42, v150
	s_add_i32 s43, 0, 0x1c000
	ds_read_b128 v[142:145], v153
	ds_read_b128 v[146:149], v153 offset:1024
	ds_read_b128 v[154:157], v153 offset:2048
	ds_read_b128 v[158:161], v153 offset:3072
	v_add_u32_e32 v153, s43, v150
	ds_read_b128 v[162:165], v153
	ds_read_b128 v[166:169], v153 offset:1024
	ds_read_b128 v[170:173], v153 offset:2048
	ds_read_b128 v[174:177], v153 offset:3072
	s_add_u32 s18, s26, 0xf0000
	s_addc_u32 s19, s27, 0
	s_mov_b32 m0, s38
	v_lshl_add_u64 v[224:225], s[18:19], 0, v[30:31]
	ds_read_b128 v[178:181], v152 offset:32768
	ds_read_b128 v[196:199], v152 offset:33792
	ds_read_b128 v[200:203], v152 offset:34816
	ds_read_b128 v[204:207], v152 offset:35840
	ds_read_b128 v[208:211], v152 offset:36864
	ds_read_b128 v[212:215], v152 offset:37888
	ds_read_b128 v[216:219], v152 offset:38912
	ds_read_b128 v[220:223], v152 offset:39936
	global_load_lds_dwordx4 v[224:225], off
	v_lshl_add_u64 v[224:225], s[18:19], 0, v[134:135]
	s_mov_b32 m0, s39
	s_nop 0
	global_load_lds_dwordx4 v[224:225], off
	s_waitcnt vmcnt(8)
	s_waitcnt lgkmcnt(0)
	s_barrier
	s_setprio 1
	s_waitcnt lgkmcnt(0)
	v_mfma_f32_16x16x32_bf16 v[130:133], v[142:145], v[178:181], v[130:133]
	v_mfma_f32_16x16x32_bf16 v[130:133], v[146:149], v[196:199], v[130:133]
	v_mfma_f32_16x16x32_bf16 v[126:129], v[158:161], v[196:199], v[126:129]
	v_mfma_f32_16x16x32_bf16 v[126:129], v[154:157], v[178:181], v[126:129]
	v_mfma_f32_16x16x32_bf16 v[110:113], v[154:157], v[200:203], v[110:113]
	v_mfma_f32_16x16x32_bf16 v[110:113], v[158:161], v[204:207], v[110:113]
	v_mfma_f32_16x16x32_bf16 v[114:117], v[146:149], v[204:207], v[114:117]
	v_mfma_f32_16x16x32_bf16 v[114:117], v[142:145], v[200:203], v[114:117]
	v_mfma_f32_16x16x32_bf16 v[98:101], v[142:145], v[208:211], v[98:101]
	v_mfma_f32_16x16x32_bf16 v[98:101], v[146:149], v[212:215], v[98:101]
	v_mfma_f32_16x16x32_bf16 v[94:97], v[158:161], v[212:215], v[94:97]
	v_mfma_f32_16x16x32_bf16 v[94:97], v[154:157], v[208:211], v[94:97]
	v_mfma_f32_16x16x32_bf16 v[78:81], v[154:157], v[216:219], v[78:81]
	v_mfma_f32_16x16x32_bf16 v[78:81], v[158:161], v[220:223], v[78:81]
	v_mfma_f32_16x16x32_bf16 v[82:85], v[146:149], v[220:223], v[82:85]
	v_mfma_f32_16x16x32_bf16 v[82:85], v[142:145], v[216:219], v[82:85]
	s_setprio 0
	s_setprio 1
	v_mfma_f32_16x16x32_bf16 v[122:125], v[162:165], v[178:181], v[122:125]
	v_mfma_f32_16x16x32_bf16 v[122:125], v[166:169], v[196:199], v[122:125]
	v_mfma_f32_16x16x32_bf16 v[118:121], v[174:177], v[196:199], v[118:121]
	v_mfma_f32_16x16x32_bf16 v[118:121], v[170:173], v[178:181], v[118:121]
	v_mfma_f32_16x16x32_bf16 v[102:105], v[170:173], v[200:203], v[102:105]
	v_mfma_f32_16x16x32_bf16 v[102:105], v[174:177], v[204:207], v[102:105]
	v_mfma_f32_16x16x32_bf16 v[106:109], v[166:169], v[204:207], v[106:109]
	v_mfma_f32_16x16x32_bf16 v[106:109], v[162:165], v[200:203], v[106:109]
	v_mfma_f32_16x16x32_bf16 v[90:93], v[162:165], v[208:211], v[90:93]
	v_mfma_f32_16x16x32_bf16 v[90:93], v[166:169], v[212:215], v[90:93]
	v_mfma_f32_16x16x32_bf16 v[86:89], v[174:177], v[212:215], v[86:89]
	v_mfma_f32_16x16x32_bf16 v[86:89], v[170:173], v[208:211], v[86:89]
	v_mfma_f32_16x16x32_bf16 v[70:73], v[170:173], v[216:219], v[70:73]
	v_mfma_f32_16x16x32_bf16 v[70:73], v[174:177], v[220:223], v[70:73]
	v_mfma_f32_16x16x32_bf16 v[74:77], v[166:169], v[220:223], v[74:77]
	v_mfma_f32_16x16x32_bf16 v[74:77], v[162:165], v[216:219], v[74:77]
	s_setprio 0
	s_barrier
; #define PG8_STAGE(bufoff, gbase, voff) do { _Pragma("unroll") for (int _i = 0; _i < 2; ++_i) \
;         __builtin_amdgcn_global_load_lds((const unsigned*)((const char*)(gbase) + (voff)[_i]), (PG8_LAS unsigned*)(lds + (bufoff) + ldsw + _i * 8192), 16, 0, 0); } while (0)
; #define PG8_LDA(dst, b, h) do { _Pragma("unroll") for (int m = 0; m < 4; ++m) _Pragma("unroll") for (int k = 0; k < 2; ++k) dst[m][k] = *(const PG8_LAS bf16x8*)(lds + PG8_SA(b, h) + aoff + m * 2048 + k * 1024); } while (0)
; #define PG8_MMA(ai, bj, At, Bt) do { __builtin_amdgcn_s_setprio(1); _Pragma("unroll") for (int m = 0; m < 4; ++m) _Pragma("unroll") for (int n = 0; n < 2; ++n) _Pragma("unroll") for (int k = 0; k < 2; ++k) \
;         acc[ai][bj][m][n] = __builtin_amdgcn_mfma_f32_16x16x32_bf16(Bt[n][k], At[m][k], acc[ai][bj][m][n], 0, 0, 0); __builtin_amdgcn_s_setprio(0); } while (0)
; #define PG8_WAIT_V(n) asm volatile("s_waitcnt vmcnt(" #n ")" ::: "memory")
; #define PG8_WAIT_L(n) asm volatile("s_waitcnt lgkmcnt(" #n ")" ::: "memory")
; #define PG8_BAR __builtin_amdgcn_s_barrier()
; #define PG8_SCHED __builtin_amdgcn_sched_barrier(0)
;     ...
;             PG8_LDA(At, 1, 1); PG8_STAGE(PG8_SB(1, 0), b3, voffB); PG8_STAGE(PG8_SB(1, 1), b3 + hstep, voffB); PG8_STAGE(PG8_SA(1, 0), a3, voffA);
;             PG8_WAIT_V(8); PG8_WAIT_L(0); PG8_BAR; PG8_MMA(1, 0, At, B0); PG8_MMA(1, 1, At, B1); PG8_BAR; PG8_SCHED;
;     ...
;         if constexpr (ALIGN_EPI) { if (wr == 0) PG8_BAR; }
	s_add_i32 s18, s42, s30
	v_lshl_add_u64 v[182:183], v[182:183], 0, s[64:65]
	s_mov_b32 m0, s18
	ds_read_b128 v[178:181], v152 offset:49152
	ds_read_b128 v[196:199], v152 offset:50176
	ds_read_b128 v[200:203], v152 offset:51200
	ds_read_b128 v[204:207], v152 offset:52224
	ds_read_b128 v[208:211], v152 offset:53248
	ds_read_b128 v[212:215], v152 offset:54272
	ds_read_b128 v[216:219], v152 offset:55296
	ds_read_b128 v[220:223], v152 offset:56320
	global_load_lds_dwordx4 v[182:183], off
	s_add_i32 m0, s18, 0x2000
	s_add_u32 s18, s24, 0x20080
	v_lshl_add_u64 v[182:183], v[186:187], 0, s[64:65]
	s_addc_u32 s19, s25, 0
	s_add_i32 s24, s43, s30
	global_load_lds_dwordx4 v[182:183], off
	v_lshl_add_u64 v[182:183], s[18:19], 0, v[32:33]
	s_mov_b32 m0, s24
	s_nop 0
	global_load_lds_dwordx4 v[182:183], off
	v_lshl_add_u64 v[182:183], s[18:19], 0, v[136:137]
	s_add_i32 m0, s24, 0x2000
	s_nop 0
	global_load_lds_dwordx4 v[182:183], off
	v_lshl_add_u64 v[182:183], v[188:189], 0, s[64:65]
	s_mov_b32 m0, s40
	s_nop 0
	global_load_lds_dwordx4 v[182:183], off
	v_lshl_add_u64 v[182:183], v[190:191], 0, s[64:65]
	s_mov_b32 m0, s41
	s_nop 0
	global_load_lds_dwordx4 v[182:183], off
	s_waitcnt vmcnt(8)
	s_waitcnt lgkmcnt(0)
	s_barrier
	s_setprio 1
	s_waitcnt lgkmcnt(0)
	v_mfma_f32_16x16x32_bf16 v[66:69], v[142:145], v[178:181], v[66:69]
	v_mfma_f32_16x16x32_bf16 v[66:69], v[146:149], v[196:199], v[66:69]
	v_mfma_f32_16x16x32_bf16 v[62:65], v[158:161], v[196:199], v[62:65]
	v_mfma_f32_16x16x32_bf16 v[62:65], v[154:157], v[178:181], v[62:65]
	v_mfma_f32_16x16x32_bf16 v[46:49], v[154:157], v[200:203], v[46:49]
	v_mfma_f32_16x16x32_bf16 v[46:49], v[158:161], v[204:207], v[46:49]
	v_mfma_f32_16x16x32_bf16 v[50:53], v[146:149], v[204:207], v[50:53]
	v_mfma_f32_16x16x32_bf16 v[50:53], v[142:145], v[200:203], v[50:53]
	v_mfma_f32_16x16x32_bf16 v[34:37], v[142:145], v[208:211], v[34:37]
	v_mfma_f32_16x16x32_bf16 v[34:37], v[146:149], v[212:215], v[34:37]
	v_mfma_f32_16x16x32_bf16 v[26:29], v[158:161], v[212:215], v[26:29]
	v_mfma_f32_16x16x32_bf16 v[26:29], v[154:157], v[208:211], v[26:29]
	v_mfma_f32_16x16x32_bf16 v[10:13], v[154:157], v[216:219], v[10:13]
	v_mfma_f32_16x16x32_bf16 v[10:13], v[158:161], v[220:223], v[10:13]
	v_mfma_f32_16x16x32_bf16 v[14:17], v[146:149], v[220:223], v[14:17]
	v_mfma_f32_16x16x32_bf16 v[14:17], v[142:145], v[216:219], v[14:17]
	s_setprio 0
	s_setprio 1
	v_mfma_f32_16x16x32_bf16 v[58:61], v[162:165], v[178:181], v[58:61]
	v_mfma_f32_16x16x32_bf16 v[58:61], v[166:169], v[196:199], v[58:61]
	v_mfma_f32_16x16x32_bf16 v[54:57], v[174:177], v[196:199], v[54:57]
	v_mfma_f32_16x16x32_bf16 v[54:57], v[170:173], v[178:181], v[54:57]
	v_mfma_f32_16x16x32_bf16 v[38:41], v[170:173], v[200:203], v[38:41]
	v_mfma_f32_16x16x32_bf16 v[38:41], v[174:177], v[204:207], v[38:41]
	v_mfma_f32_16x16x32_bf16 v[42:45], v[166:169], v[204:207], v[42:45]
	v_mfma_f32_16x16x32_bf16 v[42:45], v[162:165], v[200:203], v[42:45]
	v_mfma_f32_16x16x32_bf16 v[22:25], v[162:165], v[208:211], v[22:25]
	v_mfma_f32_16x16x32_bf16 v[22:25], v[166:169], v[212:215], v[22:25]
	v_mfma_f32_16x16x32_bf16 v[18:21], v[174:177], v[212:215], v[18:21]
	v_mfma_f32_16x16x32_bf16 v[18:21], v[170:173], v[208:211], v[18:21]
	v_mfma_f32_16x16x32_bf16 v[2:5], v[170:173], v[216:219], v[2:5]
	v_mfma_f32_16x16x32_bf16 v[2:5], v[174:177], v[220:223], v[2:5]
	v_mfma_f32_16x16x32_bf16 v[6:9], v[166:169], v[220:223], v[6:9]
	v_mfma_f32_16x16x32_bf16 v[6:9], v[162:165], v[216:219], v[6:9]
	s_setprio 0
	s_barrier
	s_add_i32 s78, s78, 2
	s_add_u32 s48, s48, 0x100
	s_addc_u32 s74, s74, 0
	s_cmp_gt_u32 s78, 5
	s_mov_b64 s[18:19], s[4:5]
	s_cbranch_scc0 .LBB0_748
	s_and_b64 vcc, exec, s[8:9]
	s_cbranch_vccz .LBB0_751
	s_barrier

; #define PG8_STAGE(bufoff, gbase, voff) do { _Pragma("unroll") for (int _i = 0; _i < 2; ++_i) \
;         __builtin_amdgcn_global_load_lds((const unsigned*)((const char*)(gbase) + (voff)[_i]), (PG8_LAS unsigned*)(lds + (bufoff) + ldsw + _i * 8192), 16, 0, 0); } while (0)
; #define PG8_LDA(dst, b, h) do { _Pragma("unroll") for (int m = 0; m < 4; ++m) _Pragma("unroll") for (int k = 0; k < 2; ++k) dst[m][k] = *(const PG8_LAS bf16x8*)(lds + PG8_SA(b, h) + aoff + m * 2048 + k * 1024); } while (0)
; #define PG8_LDB(dst, b, h) do { _Pragma("unroll") for (int n = 0; n < 2; ++n) _Pragma("unroll") for (int k = 0; k < 2; ++k) dst[n][k] = *(const PG8_LAS bf16x8*)(lds + PG8_SB(b, h) + boff + n * 2048 + k * 1024); } while (0)
; #define PG8_MMA(ai, bj, At, Bt) do { __builtin_amdgcn_s_setprio(1); _Pragma("unroll") for (int m = 0; m < 4; ++m) _Pragma("unroll") for (int n = 0; n < 2; ++n) _Pragma("unroll") for (int k = 0; k < 2; ++k) \
;         acc[ai][bj][m][n] = __builtin_amdgcn_mfma_f32_16x16x32_bf16(Bt[n][k], At[m][k], acc[ai][bj][m][n], 0, 0, 0); __builtin_amdgcn_s_setprio(0); } while (0)
; #define PG8_WAIT_V(n) asm volatile("s_waitcnt vmcnt(" #n ")" ::: "memory")
; #define PG8_BAR __builtin_amdgcn_s_barrier()
;     ...
;         const char* nA = has_next ? (const char*)g.A + (size_t)nxt.pm * tstepA + (size_t)nxt.k0 * kstep : cA; const char* nB = has_next ? (const char*)g.Bt + (size_t)nxt.pn * tstep + (size_t)nxt.k0 * kstep : cB;
;         for (int t = 0; t < nt; t += 2) {
;             const bool last = (t == nt - 2);
;             const char* a1 = cA + (size_t)(t + 1) * kstep;
;             const char* a2 = last ? nA : cA + (size_t)(t + 2) * kstep; const char* b2 = last ? nB : cB + (size_t)(t + 2) * kstep;
;             const char* a3 = a2 + kstep; const char* b3 = b2 + kstep;
;             if (last && has_next) S.a_ready(nxt);
;             if constexpr (SP2) {
;             PG8_LDB(B0, 0, 0); PG8_LDB(B1, 0, 1); PG8_SCHED; PG8_LDA(At, 0, 0); PG8_STAGE(PG8_SA(1, 1), a1 + hstepA, voffA);
;             PG8_WAIT_V(8); PG8_WAIT_L(0); PG8_BAR; PG8_MMA(0, 0, At, B0); PG8_MMA(0, 1, At, B1); PG8_BAR; PG8_SCHED;
;             PG8_LDA(At, 0, 1); PG8_STAGE(PG8_SB(0, 0), b2, voffB); PG8_STAGE(PG8_SB(0, 1), b2 + hstep, voffB); PG8_STAGE(PG8_SA(0, 0), a2, voffA);
;             PG8_WAIT_V(8); PG8_WAIT_L(0); PG8_BAR; PG8_MMA(1, 0, At, B0); PG8_MMA(1, 1, At, B1); PG8_BAR; PG8_SCHED;
.LBB0_766:
	s_add_u32 s29, s24, s28
	s_addc_u32 s42, s25, 0
	s_add_u32 s30, s29, 0x100
	s_addc_u32 s31, s42, 0
	s_and_b64 s[6:7], s[26:27], exec
	s_cselect_b32 s31, s15, s31
	s_cselect_b32 s30, s14, s30
	s_add_u32 s6, s22, s28
	s_addc_u32 s7, s23, 0
	s_add_u32 s28, s6, 0x100
	s_addc_u32 s38, s7, 0
	s_add_i32 s46, 0, 0x10000
	s_and_b64 s[6:7], s[26:27], exec
	s_cselect_b32 s39, s13, s38
	s_cselect_b32 s38, s33, s28
	s_add_i32 s7, 0, 0x14000
	s_add_u32 s92, s29, 0xf0080
	s_addc_u32 s93, s42, 0
	s_add_i32 s42, s46, s53
	s_add_i32 m0, s19, 0xc000
	s_add_i32 s47, s19, 0xe000
	s_add_i32 s6, s42, 0x2000
	v_add_u32_e32 v149, s46, v146
	s_add_u32 s90, s38, 0x10000
	ds_read_b128 v[138:141], v149
	ds_read_b128 v[142:145], v149 offset:1024
	ds_read_b128 v[150:153], v149 offset:2048
	ds_read_b128 v[154:157], v149 offset:3072
	v_add_u32_e32 v149, s7, v146
	s_addc_u32 s91, s39, 0
	s_add_i32 s43, s7, s53
	ds_read_b128 v[158:161], v149
	ds_read_b128 v[162:165], v149 offset:1024
	ds_read_b128 v[166:169], v149 offset:2048
	ds_read_b128 v[170:173], v149 offset:3072
	s_add_i32 s75, s43, 0x2000
	s_add_i32 vcc_hi, 0, 0x18000
	s_add_i32 s49, 0, 0x1c000
	s_add_u32 s28, s30, 0xf0000
	s_addc_u32 s29, s31, 0
	s_add_i32 vcc_lo, vcc_hi, s53
	s_add_i32 s51, vcc_lo, 0x2000
	s_add_u32 s26, s38, 0x10080
	s_addc_u32 s27, s39, 0
	s_add_i32 s7, s49, s53
	s_add_i32 s46, s7, 0x2000
	v_lshl_add_u64 v[182:183], s[92:93], 0, v[136:137]
	ds_read_b128 v[174:177], v148
	ds_read_b128 v[178:181], v148 offset:1024
	ds_read_b128 v[196:199], v148 offset:2048
	ds_read_b128 v[200:203], v148 offset:3072
	ds_read_b128 v[204:207], v148 offset:4096
	ds_read_b128 v[208:211], v148 offset:5120
	ds_read_b128 v[212:215], v148 offset:6144
	ds_read_b128 v[216:219], v148 offset:7168
	global_load_lds_dwordx4 v[182:183], off
	v_lshl_add_u64 v[182:183], s[92:93], 0, v[134:135]
	s_mov_b32 m0, s47
	s_nop 0
	global_load_lds_dwordx4 v[182:183], off
	s_waitcnt vmcnt(8)
	s_waitcnt lgkmcnt(0)
	s_barrier
	s_setprio 1
	s_waitcnt lgkmcnt(0)
	v_mfma_f32_16x16x32_bf16 v[130:133], v[138:141], v[174:177], v[130:133]
	v_mfma_f32_16x16x32_bf16 v[130:133], v[142:145], v[178:181], v[130:133]
	v_mfma_f32_16x16x32_bf16 v[126:129], v[154:157], v[178:181], v[126:129]
	v_mfma_f32_16x16x32_bf16 v[126:129], v[150:153], v[174:177], v[126:129]
	v_mfma_f32_16x16x32_bf16 v[110:113], v[150:153], v[196:199], v[110:113]
	v_mfma_f32_16x16x32_bf16 v[110:113], v[154:157], v[200:203], v[110:113]
	v_mfma_f32_16x16x32_bf16 v[114:117], v[142:145], v[200:203], v[114:117]
	v_mfma_f32_16x16x32_bf16 v[114:117], v[138:141], v[196:199], v[114:117]
	v_mfma_f32_16x16x32_bf16 v[98:101], v[138:141], v[204:207], v[98:101]
	v_mfma_f32_16x16x32_bf16 v[98:101], v[142:145], v[208:211], v[98:101]
	v_mfma_f32_16x16x32_bf16 v[94:97], v[154:157], v[208:211], v[94:97]
	v_mfma_f32_16x16x32_bf16 v[94:97], v[150:153], v[204:207], v[94:97]
	v_mfma_f32_16x16x32_bf16 v[78:81], v[150:153], v[212:215], v[78:81]
	v_mfma_f32_16x16x32_bf16 v[78:81], v[154:157], v[216:219], v[78:81]
	v_mfma_f32_16x16x32_bf16 v[82:85], v[142:145], v[216:219], v[82:85]
	v_mfma_f32_16x16x32_bf16 v[82:85], v[138:141], v[212:215], v[82:85]
	s_setprio 0
	s_setprio 1
	v_mfma_f32_16x16x32_bf16 v[122:125], v[158:161], v[174:177], v[122:125]
	v_mfma_f32_16x16x32_bf16 v[122:125], v[162:165], v[178:181], v[122:125]
	v_mfma_f32_16x16x32_bf16 v[118:121], v[170:173], v[178:181], v[118:121]
	v_mfma_f32_16x16x32_bf16 v[118:121], v[166:169], v[174:177], v[118:121]
	v_mfma_f32_16x16x32_bf16 v[102:105], v[166:169], v[196:199], v[102:105]
	v_mfma_f32_16x16x32_bf16 v[102:105], v[170:173], v[200:203], v[102:105]
	v_mfma_f32_16x16x32_bf16 v[106:109], v[162:165], v[200:203], v[106:109]
	v_mfma_f32_16x16x32_bf16 v[106:109], v[158:161], v[196:199], v[106:109]
	v_mfma_f32_16x16x32_bf16 v[90:93], v[158:161], v[204:207], v[90:93]
	v_mfma_f32_16x16x32_bf16 v[90:93], v[162:165], v[208:211], v[90:93]
	v_mfma_f32_16x16x32_bf16 v[86:89], v[170:173], v[208:211], v[86:89]
	v_mfma_f32_16x16x32_bf16 v[86:89], v[166:169], v[204:207], v[86:89]
	v_mfma_f32_16x16x32_bf16 v[70:73], v[166:169], v[212:215], v[70:73]
	v_mfma_f32_16x16x32_bf16 v[70:73], v[170:173], v[216:219], v[70:73]
	v_mfma_f32_16x16x32_bf16 v[74:77], v[162:165], v[216:219], v[74:77]
	v_mfma_f32_16x16x32_bf16 v[74:77], v[158:161], v[212:215], v[74:77]
	s_setprio 0
	s_barrier
	s_mov_b32 m0, s42
	v_lshl_add_u64 v[182:183], s[38:39], 0, v[32:33]
	ds_read_b128 v[174:177], v148 offset:16384
	ds_read_b128 v[178:181], v148 offset:17408
	ds_read_b128 v[196:199], v148 offset:18432
	ds_read_b128 v[200:203], v148 offset:19456
	ds_read_b128 v[204:207], v148 offset:20480
	ds_read_b128 v[208:211], v148 offset:21504
	ds_read_b128 v[212:215], v148 offset:22528
	ds_read_b128 v[216:219], v148 offset:23552
	global_load_lds_dwordx4 v[182:183], off
	v_lshl_add_u64 v[186:187], s[38:39], 0, v[30:31]
	s_mov_b32 m0, s6
	v_lshl_add_u64 v[188:189], s[90:91], 0, v[32:33]
	global_load_lds_dwordx4 v[186:187], off
	s_mov_b32 m0, s43
	v_lshl_add_u64 v[190:191], s[30:31], 0, v[134:135]
	global_load_lds_dwordx4 v[188:189], off
	v_lshl_add_u64 v[188:189], s[90:91], 0, v[30:31]
	s_mov_b32 m0, s75
	s_nop 0
	global_load_lds_dwordx4 v[188:189], off
	v_lshl_add_u64 v[188:189], s[30:31], 0, v[136:137]
	s_mov_b32 m0, s19
	s_nop 0
	global_load_lds_dwordx4 v[188:189], off
	s_mov_b32 m0, s74
	s_nop 0
	global_load_lds_dwordx4 v[190:191], off
	s_waitcnt vmcnt(8)
	s_waitcnt lgkmcnt(0)
	s_barrier
; #define PG8_STAGE(bufoff, gbase, voff) do { _Pragma("unroll") for (int _i = 0; _i < 2; ++_i) \
;         __builtin_amdgcn_global_load_lds((const unsigned*)((const char*)(gbase) + (voff)[_i]), (PG8_LAS unsigned*)(lds + (bufoff) + ldsw + _i * 8192), 16, 0, 0); } while (0)
; #define PG8_LDA(dst, b, h) do { _Pragma("unroll") for (int m = 0; m < 4; ++m) _Pragma("unroll") for (int k = 0; k < 2; ++k) dst[m][k] = *(const PG8_LAS bf16x8*)(lds + PG8_SA(b, h) + aoff + m * 2048 + k * 1024); } while (0)
; #define PG8_LDB(dst, b, h) do { _Pragma("unroll") for (int n = 0; n < 2; ++n) _Pragma("unroll") for (int k = 0; k < 2; ++k) dst[n][k] = *(const PG8_LAS bf16x8*)(lds + PG8_SB(b, h) + boff + n * 2048 + k * 1024); } while (0)
; #define PG8_MMA(ai, bj, At, Bt) do { __builtin_amdgcn_s_setprio(1); _Pragma("unroll") for (int m = 0; m < 4; ++m) _Pragma("unroll") for (int n = 0; n < 2; ++n) _Pragma("unroll") for (int k = 0; k < 2; ++k) \
;         acc[ai][bj][m][n] = __builtin_amdgcn_mfma_f32_16x16x32_bf16(Bt[n][k], At[m][k], acc[ai][bj][m][n], 0, 0, 0); __builtin_amdgcn_s_setprio(0); } while (0)
; #define PG8_WAIT_V(n) asm volatile("s_waitcnt vmcnt(" #n ")" ::: "memory")
; #define PG8_WAIT_L(n) asm volatile("s_waitcnt lgkmcnt(" #n ")" ::: "memory")
; #define PG8_BAR __builtin_amdgcn_s_barrier()
; #define PG8_SCHED __builtin_amdgcn_sched_barrier(0)
;     ...
;             PG8_WAIT_V(8); PG8_WAIT_L(0); PG8_BAR; PG8_MMA(1, 0, At, B0); PG8_MMA(1, 1, At, B1); PG8_BAR; PG8_SCHED;
;             PG8_LDB(B0, 1, 0); PG8_LDB(B1, 1, 1); PG8_SCHED; PG8_LDA(At, 1, 0); PG8_STAGE(PG8_SA(0, 1), a2 + hstepA, voffA);
;             PG8_WAIT_V(8); PG8_WAIT_L(0); PG8_BAR; PG8_MMA(0, 0, At, B0); PG8_MMA(0, 1, At, B1); PG8_BAR; PG8_SCHED;
	s_setprio 1
	s_waitcnt lgkmcnt(0)
	v_mfma_f32_16x16x32_bf16 v[66:69], v[138:141], v[174:177], v[66:69]
	v_mfma_f32_16x16x32_bf16 v[66:69], v[142:145], v[178:181], v[66:69]
	v_mfma_f32_16x16x32_bf16 v[62:65], v[154:157], v[178:181], v[62:65]
	v_mfma_f32_16x16x32_bf16 v[62:65], v[150:153], v[174:177], v[62:65]
	v_mfma_f32_16x16x32_bf16 v[46:49], v[150:153], v[196:199], v[46:49]
	v_mfma_f32_16x16x32_bf16 v[46:49], v[154:157], v[200:203], v[46:49]
	v_mfma_f32_16x16x32_bf16 v[50:53], v[142:145], v[200:203], v[50:53]
	v_mfma_f32_16x16x32_bf16 v[50:53], v[138:141], v[196:199], v[50:53]
	v_mfma_f32_16x16x32_bf16 v[34:37], v[138:141], v[204:207], v[34:37]
	v_mfma_f32_16x16x32_bf16 v[34:37], v[142:145], v[208:211], v[34:37]
	v_mfma_f32_16x16x32_bf16 v[26:29], v[154:157], v[208:211], v[26:29]
	v_mfma_f32_16x16x32_bf16 v[26:29], v[150:153], v[204:207], v[26:29]
	v_mfma_f32_16x16x32_bf16 v[10:13], v[150:153], v[212:215], v[10:13]
	v_mfma_f32_16x16x32_bf16 v[10:13], v[154:157], v[216:219], v[10:13]
	v_mfma_f32_16x16x32_bf16 v[14:17], v[142:145], v[216:219], v[14:17]
	v_mfma_f32_16x16x32_bf16 v[14:17], v[138:141], v[212:215], v[14:17]
	s_setprio 0
	s_setprio 1
	v_mfma_f32_16x16x32_bf16 v[58:61], v[158:161], v[174:177], v[58:61]
	v_mfma_f32_16x16x32_bf16 v[58:61], v[162:165], v[178:181], v[58:61]
	v_mfma_f32_16x16x32_bf16 v[54:57], v[170:173], v[178:181], v[54:57]
	v_mfma_f32_16x16x32_bf16 v[54:57], v[166:169], v[174:177], v[54:57]
	v_mfma_f32_16x16x32_bf16 v[38:41], v[166:169], v[196:199], v[38:41]
	v_mfma_f32_16x16x32_bf16 v[38:41], v[170:173], v[200:203], v[38:41]
	v_mfma_f32_16x16x32_bf16 v[42:45], v[162:165], v[200:203], v[42:45]
	v_mfma_f32_16x16x32_bf16 v[42:45], v[158:161], v[196:199], v[42:45]
	v_mfma_f32_16x16x32_bf16 v[22:25], v[158:161], v[204:207], v[22:25]
	v_mfma_f32_16x16x32_bf16 v[22:25], v[162:165], v[208:211], v[22:25]
	v_mfma_f32_16x16x32_bf16 v[18:21], v[170:173], v[208:211], v[18:21]
	v_mfma_f32_16x16x32_bf16 v[18:21], v[166:169], v[204:207], v[18:21]
	v_mfma_f32_16x16x32_bf16 v[2:5], v[166:169], v[212:215], v[2:5]
	v_mfma_f32_16x16x32_bf16 v[2:5], v[170:173], v[216:219], v[2:5]
	v_mfma_f32_16x16x32_bf16 v[6:9], v[162:165], v[216:219], v[6:9]
	v_mfma_f32_16x16x32_bf16 v[6:9], v[158:161], v[212:215], v[6:9]
	s_setprio 0
	s_barrier
	v_add_u32_e32 v149, vcc_hi, v146
	ds_read_b128 v[138:141], v149
	ds_read_b128 v[142:145], v149 offset:1024
	ds_read_b128 v[150:153], v149 offset:2048
	ds_read_b128 v[154:157], v149 offset:3072
	v_add_u32_e32 v149, s49, v146
	ds_read_b128 v[158:161], v149
	ds_read_b128 v[162:165], v149 offset:1024
	ds_read_b128 v[166:169], v149 offset:2048
	ds_read_b128 v[170:173], v149 offset:3072
	s_mov_b32 m0, s78
	v_lshl_add_u64 v[220:221], s[28:29], 0, v[136:137]
	ds_read_b128 v[174:177], v148 offset:32768
	ds_read_b128 v[178:181], v148 offset:33792
	ds_read_b128 v[196:199], v148 offset:34816
	ds_read_b128 v[200:203], v148 offset:35840
	ds_read_b128 v[204:207], v148 offset:36864
	ds_read_b128 v[208:211], v148 offset:37888
	ds_read_b128 v[212:215], v148 offset:38912
	ds_read_b128 v[216:219], v148 offset:39936
	global_load_lds_dwordx4 v[220:221], off
	v_lshl_add_u64 v[220:221], s[28:29], 0, v[134:135]
	s_mov_b32 m0, s79
	s_nop 0
	global_load_lds_dwordx4 v[220:221], off
	s_waitcnt vmcnt(8)
	s_waitcnt lgkmcnt(0)
	s_barrier
	s_setprio 1
	s_waitcnt lgkmcnt(0)
	v_mfma_f32_16x16x32_bf16 v[130:133], v[138:141], v[174:177], v[130:133]
	v_mfma_f32_16x16x32_bf16 v[130:133], v[142:145], v[178:181], v[130:133]
	v_mfma_f32_16x16x32_bf16 v[126:129], v[154:157], v[178:181], v[126:129]
	v_mfma_f32_16x16x32_bf16 v[126:129], v[150:153], v[174:177], v[126:129]
	v_mfma_f32_16x16x32_bf16 v[110:113], v[150:153], v[196:199], v[110:113]
	v_mfma_f32_16x16x32_bf16 v[110:113], v[154:157], v[200:203], v[110:113]
	v_mfma_f32_16x16x32_bf16 v[114:117], v[142:145], v[200:203], v[114:117]
	v_mfma_f32_16x16x32_bf16 v[114:117], v[138:141], v[196:199], v[114:117]
	v_mfma_f32_16x16x32_bf16 v[98:101], v[138:141], v[204:207], v[98:101]
	v_mfma_f32_16x16x32_bf16 v[98:101], v[142:145], v[208:211], v[98:101]
	v_mfma_f32_16x16x32_bf16 v[94:97], v[154:157], v[208:211], v[94:97]
	v_mfma_f32_16x16x32_bf16 v[94:97], v[150:153], v[204:207], v[94:97]
	v_mfma_f32_16x16x32_bf16 v[78:81], v[150:153], v[212:215], v[78:81]
	v_mfma_f32_16x16x32_bf16 v[78:81], v[154:157], v[216:219], v[78:81]
	v_mfma_f32_16x16x32_bf16 v[82:85], v[142:145], v[216:219], v[82:85]
	v_mfma_f32_16x16x32_bf16 v[82:85], v[138:141], v[212:215], v[82:85]
	s_setprio 0
	s_setprio 1
	v_mfma_f32_16x16x32_bf16 v[122:125], v[158:161], v[174:177], v[122:125]
	v_mfma_f32_16x16x32_bf16 v[122:125], v[162:165], v[178:181], v[122:125]
	v_mfma_f32_16x16x32_bf16 v[118:121], v[170:173], v[178:181], v[118:121]
	v_mfma_f32_16x16x32_bf16 v[118:121], v[166:169], v[174:177], v[118:121]
	v_mfma_f32_16x16x32_bf16 v[102:105], v[166:169], v[196:199], v[102:105]
	v_mfma_f32_16x16x32_bf16 v[102:105], v[170:173], v[200:203], v[102:105]
	v_mfma_f32_16x16x32_bf16 v[106:109], v[162:165], v[200:203], v[106:109]
	v_mfma_f32_16x16x32_bf16 v[106:109], v[158:161], v[196:199], v[106:109]
	v_mfma_f32_16x16x32_bf16 v[90:93], v[158:161], v[204:207], v[90:93]
	v_mfma_f32_16x16x32_bf16 v[90:93], v[162:165], v[208:211], v[90:93]
	v_mfma_f32_16x16x32_bf16 v[86:89], v[170:173], v[208:211], v[86:89]
	v_mfma_f32_16x16x32_bf16 v[86:89], v[166:169], v[204:207], v[86:89]
	v_mfma_f32_16x16x32_bf16 v[70:73], v[166:169], v[212:215], v[70:73]
	v_mfma_f32_16x16x32_bf16 v[70:73], v[170:173], v[216:219], v[70:73]
	v_mfma_f32_16x16x32_bf16 v[74:77], v[162:165], v[216:219], v[74:77]
	v_mfma_f32_16x16x32_bf16 v[74:77], v[158:161], v[212:215], v[74:77]
	s_setprio 0
	s_barrier
; #define PG8_STAGE(bufoff, gbase, voff) do { _Pragma("unroll") for (int _i = 0; _i < 2; ++_i) \
;         __builtin_amdgcn_global_load_lds((const unsigned*)((const char*)(gbase) + (voff)[_i]), (PG8_LAS unsigned*)(lds + (bufoff) + ldsw + _i * 8192), 16, 0, 0); } while (0)
; #define PG8_LDA(dst, b, h) do { _Pragma("unroll") for (int m = 0; m < 4; ++m) _Pragma("unroll") for (int k = 0; k < 2; ++k) dst[m][k] = *(const PG8_LAS bf16x8*)(lds + PG8_SA(b, h) + aoff + m * 2048 + k * 1024); } while (0)
; #define PG8_MMA(ai, bj, At, Bt) do { __builtin_amdgcn_s_setprio(1); _Pragma("unroll") for (int m = 0; m < 4; ++m) _Pragma("unroll") for (int n = 0; n < 2; ++n) _Pragma("unroll") for (int k = 0; k < 2; ++k) \
;         acc[ai][bj][m][n] = __builtin_amdgcn_mfma_f32_16x16x32_bf16(Bt[n][k], At[m][k], acc[ai][bj][m][n], 0, 0, 0); __builtin_amdgcn_s_setprio(0); } while (0)
; #define PG8_WAIT_V(n) asm volatile("s_waitcnt vmcnt(" #n ")" ::: "memory")
; #define PG8_WAIT_L(n) asm volatile("s_waitcnt lgkmcnt(" #n ")" ::: "memory")
; #define PG8_BAR __builtin_amdgcn_s_barrier()
; #define PG8_SCHED __builtin_amdgcn_sched_barrier(0)
;     ...
;             PG8_LDA(At, 1, 1); PG8_STAGE(PG8_SB(1, 0), b3, voffB); PG8_STAGE(PG8_SB(1, 1), b3 + hstep, voffB); PG8_STAGE(PG8_SA(1, 0), a3, voffA);
;             PG8_WAIT_V(8); PG8_WAIT_L(0); PG8_BAR; PG8_MMA(1, 0, At, B0); PG8_MMA(1, 1, At, B1); PG8_BAR; PG8_SCHED;
;     ...
;         if constexpr (ALIGN_EPI) { if (wr == 0) PG8_BAR; }
	s_mov_b32 m0, vcc_lo
	v_lshl_add_u64 v[182:183], v[182:183], 0, s[64:65]
	ds_read_b128 v[174:177], v148 offset:49152
	ds_read_b128 v[178:181], v148 offset:50176
	ds_read_b128 v[196:199], v148 offset:51200
	ds_read_b128 v[200:203], v148 offset:52224
	ds_read_b128 v[204:207], v148 offset:53248
	ds_read_b128 v[208:211], v148 offset:54272
	ds_read_b128 v[212:215], v148 offset:55296
	ds_read_b128 v[216:219], v148 offset:56320
	global_load_lds_dwordx4 v[182:183], off
	v_lshl_add_u64 v[182:183], v[186:187], 0, s[64:65]
	s_mov_b32 m0, s51
	s_nop 0
	global_load_lds_dwordx4 v[182:183], off
	v_lshl_add_u64 v[182:183], s[26:27], 0, v[32:33]
	s_mov_b32 m0, s7
	s_nop 0
	global_load_lds_dwordx4 v[182:183], off
	v_lshl_add_u64 v[182:183], s[26:27], 0, v[30:31]
	s_mov_b32 m0, s46
	s_nop 0
	global_load_lds_dwordx4 v[182:183], off
	v_lshl_add_u64 v[182:183], v[188:189], 0, s[64:65]
	s_mov_b32 m0, s94
	s_nop 0
	global_load_lds_dwordx4 v[182:183], off
	v_lshl_add_u64 v[182:183], v[190:191], 0, s[64:65]
	s_mov_b32 m0, s95
	s_nop 0
	global_load_lds_dwordx4 v[182:183], off
	s_waitcnt vmcnt(8)
	s_waitcnt lgkmcnt(0)
	s_barrier
	s_setprio 1
	s_waitcnt lgkmcnt(0)
	v_mfma_f32_16x16x32_bf16 v[66:69], v[138:141], v[174:177], v[66:69]
	v_mfma_f32_16x16x32_bf16 v[66:69], v[142:145], v[178:181], v[66:69]
	v_mfma_f32_16x16x32_bf16 v[62:65], v[154:157], v[178:181], v[62:65]
	v_mfma_f32_16x16x32_bf16 v[62:65], v[150:153], v[174:177], v[62:65]
	v_mfma_f32_16x16x32_bf16 v[46:49], v[150:153], v[196:199], v[46:49]
	v_mfma_f32_16x16x32_bf16 v[46:49], v[154:157], v[200:203], v[46:49]
	v_mfma_f32_16x16x32_bf16 v[50:53], v[142:145], v[200:203], v[50:53]
	v_mfma_f32_16x16x32_bf16 v[50:53], v[138:141], v[196:199], v[50:53]
	v_mfma_f32_16x16x32_bf16 v[34:37], v[138:141], v[204:207], v[34:37]
	v_mfma_f32_16x16x32_bf16 v[34:37], v[142:145], v[208:211], v[34:37]
	v_mfma_f32_16x16x32_bf16 v[26:29], v[154:157], v[208:211], v[26:29]
	v_mfma_f32_16x16x32_bf16 v[26:29], v[150:153], v[204:207], v[26:29]
	v_mfma_f32_16x16x32_bf16 v[10:13], v[150:153], v[212:215], v[10:13]
	v_mfma_f32_16x16x32_bf16 v[10:13], v[154:157], v[216:219], v[10:13]
	v_mfma_f32_16x16x32_bf16 v[14:17], v[142:145], v[216:219], v[14:17]
	v_mfma_f32_16x16x32_bf16 v[14:17], v[138:141], v[212:215], v[14:17]
	s_setprio 0
	s_setprio 1
	v_mfma_f32_16x16x32_bf16 v[58:61], v[158:161], v[174:177], v[58:61]
	v_mfma_f32_16x16x32_bf16 v[58:61], v[162:165], v[178:181], v[58:61]
	v_mfma_f32_16x16x32_bf16 v[54:57], v[170:173], v[178:181], v[54:57]
	v_mfma_f32_16x16x32_bf16 v[54:57], v[166:169], v[174:177], v[54:57]
	v_mfma_f32_16x16x32_bf16 v[38:41], v[166:169], v[196:199], v[38:41]
	v_mfma_f32_16x16x32_bf16 v[38:41], v[170:173], v[200:203], v[38:41]
	v_mfma_f32_16x16x32_bf16 v[42:45], v[162:165], v[200:203], v[42:45]
	v_mfma_f32_16x16x32_bf16 v[42:45], v[158:161], v[196:199], v[42:45]
	v_mfma_f32_16x16x32_bf16 v[22:25], v[158:161], v[204:207], v[22:25]
	v_mfma_f32_16x16x32_bf16 v[22:25], v[162:165], v[208:211], v[22:25]
	v_mfma_f32_16x16x32_bf16 v[18:21], v[170:173], v[208:211], v[18:21]
	v_mfma_f32_16x16x32_bf16 v[18:21], v[166:169], v[204:207], v[18:21]
	v_mfma_f32_16x16x32_bf16 v[2:5], v[166:169], v[212:215], v[2:5]
	v_mfma_f32_16x16x32_bf16 v[2:5], v[170:173], v[216:219], v[2:5]
	v_mfma_f32_16x16x32_bf16 v[6:9], v[162:165], v[216:219], v[6:9]
	v_mfma_f32_16x16x32_bf16 v[6:9], v[158:161], v[212:215], v[6:9]
	s_setprio 0
	s_barrier
	s_movk_i32 s28, 0x100
	s_andn2_b64 vcc, exec, s[4:5]
	s_mov_b64 s[26:27], -1
	s_mov_b64 s[4:5], 0
	s_cbranch_vccz .LBB0_766
	s_and_b64 vcc, exec, s[10:11]
	s_cbranch_vccz .LBB0_769
	s_barrier

; #define PG8_STAGE(bufoff, gbase, voff) do { _Pragma("unroll") for (int _i = 0; _i < 2; ++_i) \
;         __builtin_amdgcn_global_load_lds((const unsigned*)((const char*)(gbase) + (voff)[_i]), (PG8_LAS unsigned*)(lds + (bufoff) + ldsw + _i * 8192), 16, 0, 0); } while (0)
; #define PG8_LDA(dst, b, h) do { _Pragma("unroll") for (int m = 0; m < 4; ++m) _Pragma("unroll") for (int k = 0; k < 2; ++k) dst[m][k] = *(const PG8_LAS bf16x8*)(lds + PG8_SA(b, h) + aoff + m * 2048 + k * 1024); } while (0)
; #define PG8_LDB(dst, b, h) do { _Pragma("unroll") for (int n = 0; n < 2; ++n) _Pragma("unroll") for (int k = 0; k < 2; ++k) dst[n][k] = *(const PG8_LAS bf16x8*)(lds + PG8_SB(b, h) + boff + n * 2048 + k * 1024); } while (0)
; #define PG8_MMA(ai, bj, At, Bt) do { __builtin_amdgcn_s_setprio(1); _Pragma("unroll") for (int m = 0; m < 4; ++m) _Pragma("unroll") for (int n = 0; n < 2; ++n) _Pragma("unroll") for (int k = 0; k < 2; ++k) \
;         acc[ai][bj][m][n] = __builtin_amdgcn_mfma_f32_16x16x32_bf16(Bt[n][k], At[m][k], acc[ai][bj][m][n], 0, 0, 0); __builtin_amdgcn_s_setprio(0); } while (0)
; #define PG8_WAIT_V(n) asm volatile("s_waitcnt vmcnt(" #n ")" ::: "memory")
; #define PG8_WAIT_L(n) asm volatile("s_waitcnt lgkmcnt(" #n ")" ::: "memory")
; #define PG8_BAR __builtin_amdgcn_s_barrier()
; #define PG8_SCHED __builtin_amdgcn_sched_barrier(0)
;     ...
;             const bool last = (t == nt - 2);
;             const char* a1 = cA + (size_t)(t + 1) * kstep;
;             const char* a2 = last ? nA : cA + (size_t)(t + 2) * kstep; const char* b2 = last ? nB : cB + (size_t)(t + 2) * kstep;
;             const char* a3 = a2 + kstep; const char* b3 = b2 + kstep;
;             if (last && has_next) S.a_ready(nxt);
;             if constexpr (SP2) {
;             PG8_LDB(B0, 0, 0); PG8_LDB(B1, 0, 1); PG8_SCHED; PG8_LDA(At, 0, 0); PG8_STAGE(PG8_SA(1, 1), a1 + hstepA, voffA);
;             PG8_WAIT_V(8); PG8_WAIT_L(0); PG8_BAR; PG8_MMA(0, 0, At, B0); PG8_MMA(0, 1, At, B1); PG8_BAR; PG8_SCHED;
;             PG8_LDA(At, 0, 1); PG8_STAGE(PG8_SB(0, 0), b2, voffB); PG8_STAGE(PG8_SB(0, 1), b2 + hstep, voffB); PG8_STAGE(PG8_SA(0, 0), a2, voffA);
;             PG8_WAIT_V(8); PG8_WAIT_L(0); PG8_BAR; PG8_MMA(1, 0, At, B0); PG8_MMA(1, 1, At, B1); PG8_BAR; PG8_SCHED;
.LBB0_1064:
	s_add_u32 s30, s28, 0x100
	s_addc_u32 s31, s29, 0
	s_add_i32 s23, 0, 0x10000
	s_cmp_eq_u32 s40, s19
	s_cselect_b32 s93, s91, s31
	s_cselect_b32 s92, s90, s30
	v_add_u32_e32 v32, s23, v239
	s_cselect_b32 s39, s95, s17
	s_cselect_b32 s38, s94, s9
	s_add_i32 s25, 0, 0x14000
	ds_read_b128 v[72:75], v32
	ds_read_b128 v[76:79], v32 offset:1024
	ds_read_b128 v[80:83], v32 offset:2048
	ds_read_b128 v[88:91], v32 offset:3072
	v_add_u32_e32 v32, s25, v239
	ds_read_b128 v[152:155], v32
	ds_read_b128 v[156:159], v32 offset:1024
	ds_read_b128 v[160:163], v32 offset:2048
	ds_read_b128 v[164:167], v32 offset:3072
	v_lshl_add_u64 v[34:35], s[28:29], 0, v[196:197]
	s_add_i32 m0, s56, 0xc000
	ds_read_b128 v[168:171], v251
	ds_read_b128 v[172:175], v251 offset:1024
	ds_read_b128 v[176:179], v251 offset:2048
	ds_read_b128 v[200:203], v251 offset:3072
	ds_read_b128 v[204:207], v251 offset:4096
	ds_read_b128 v[208:211], v251 offset:5120
	ds_read_b128 v[212:215], v251 offset:6144
	ds_read_b128 v[216:219], v251 offset:7168
	global_load_lds_dwordx4 v[34:35], off
	v_lshl_add_u64 v[34:35], s[28:29], 0, v[198:199]
	s_add_i32 m0, s56, 0xe000
	s_nop 0
	global_load_lds_dwordx4 v[34:35], off
	s_waitcnt vmcnt(8)
	s_waitcnt lgkmcnt(0)
	s_barrier
	s_setprio 1
	s_waitcnt lgkmcnt(0)
	v_mfma_f32_16x16x32_bf16 v[84:87], v[72:75], v[168:171], v[84:87]
	v_mfma_f32_16x16x32_bf16 v[84:87], v[76:79], v[172:175], v[84:87]
	v_mfma_f32_16x16x32_bf16 v[148:151], v[88:91], v[172:175], v[148:151]
	v_mfma_f32_16x16x32_bf16 v[148:151], v[80:83], v[168:171], v[148:151]
	v_mfma_f32_16x16x32_bf16 v[132:135], v[80:83], v[176:179], v[132:135]
	v_mfma_f32_16x16x32_bf16 v[132:135], v[88:91], v[200:203], v[132:135]
	v_mfma_f32_16x16x32_bf16 v[136:139], v[76:79], v[200:203], v[136:139]
	v_mfma_f32_16x16x32_bf16 v[136:139], v[72:75], v[176:179], v[136:139]
	v_mfma_f32_16x16x32_bf16 v[120:123], v[72:75], v[204:207], v[120:123]
	v_mfma_f32_16x16x32_bf16 v[120:123], v[76:79], v[208:211], v[120:123]
	v_mfma_f32_16x16x32_bf16 v[116:119], v[88:91], v[208:211], v[116:119]
	v_mfma_f32_16x16x32_bf16 v[116:119], v[80:83], v[204:207], v[116:119]
	v_mfma_f32_16x16x32_bf16 v[100:103], v[80:83], v[212:215], v[100:103]
	v_mfma_f32_16x16x32_bf16 v[100:103], v[88:91], v[216:219], v[100:103]
	v_mfma_f32_16x16x32_bf16 v[104:107], v[76:79], v[216:219], v[104:107]
	v_mfma_f32_16x16x32_bf16 v[104:107], v[72:75], v[212:215], v[104:107]
	s_setprio 0
	s_setprio 1
	v_mfma_f32_16x16x32_bf16 v[144:147], v[152:155], v[168:171], v[144:147]
	v_mfma_f32_16x16x32_bf16 v[144:147], v[156:159], v[172:175], v[144:147]
	v_mfma_f32_16x16x32_bf16 v[140:143], v[164:167], v[172:175], v[140:143]
	v_mfma_f32_16x16x32_bf16 v[140:143], v[160:163], v[168:171], v[140:143]
	v_mfma_f32_16x16x32_bf16 v[124:127], v[160:163], v[176:179], v[124:127]
	v_mfma_f32_16x16x32_bf16 v[124:127], v[164:167], v[200:203], v[124:127]
	v_mfma_f32_16x16x32_bf16 v[128:131], v[156:159], v[200:203], v[128:131]
	v_mfma_f32_16x16x32_bf16 v[128:131], v[152:155], v[176:179], v[128:131]
	v_mfma_f32_16x16x32_bf16 v[112:115], v[152:155], v[204:207], v[112:115]
	v_mfma_f32_16x16x32_bf16 v[112:115], v[156:159], v[208:211], v[112:115]
	v_mfma_f32_16x16x32_bf16 v[108:111], v[164:167], v[208:211], v[108:111]
	v_mfma_f32_16x16x32_bf16 v[108:111], v[160:163], v[204:207], v[108:111]
	v_mfma_f32_16x16x32_bf16 v[92:95], v[160:163], v[212:215], v[92:95]
	v_mfma_f32_16x16x32_bf16 v[92:95], v[164:167], v[216:219], v[92:95]
	v_mfma_f32_16x16x32_bf16 v[96:99], v[156:159], v[216:219], v[96:99]
	v_mfma_f32_16x16x32_bf16 v[96:99], v[152:155], v[212:215], v[96:99]
	s_setprio 0
	s_barrier
	s_add_i32 s23, s23, s3
	v_lshl_add_u64 v[186:187], s[38:39], 0, v[30:31]
	s_mov_b32 m0, s23
	ds_read_b128 v[168:171], v251 offset:16384
	ds_read_b128 v[172:175], v251 offset:17408
	ds_read_b128 v[176:179], v251 offset:18432
	ds_read_b128 v[200:203], v251 offset:19456
	ds_read_b128 v[204:207], v251 offset:20480
	ds_read_b128 v[208:211], v251 offset:21504
	ds_read_b128 v[212:215], v251 offset:22528
	ds_read_b128 v[216:219], v251 offset:23552
	global_load_lds_dwordx4 v[186:187], off
	s_add_i32 m0, s23, 0x2000
	s_add_u32 s28, s38, 0x80000
	v_lshl_add_u64 v[188:189], s[38:39], 0, v[180:181]
	s_addc_u32 s29, s39, 0
	s_add_i32 s23, s25, s3
	global_load_lds_dwordx4 v[188:189], off
	v_lshl_add_u64 v[34:35], s[28:29], 0, v[30:31]
	s_mov_b32 m0, s23
	v_lshl_add_u64 v[190:191], s[92:93], 0, v[30:31]
	global_load_lds_dwordx4 v[34:35], off
	v_lshl_add_u64 v[34:35], s[28:29], 0, v[180:181]
	s_add_i32 m0, s23, 0x2000
	v_lshl_add_u64 v[220:221], s[92:93], 0, v[180:181]
	global_load_lds_dwordx4 v[34:35], off
	s_mov_b32 m0, s56
	s_nop 0
	global_load_lds_dwordx4 v[190:191], off
	s_mov_b32 m0, s41
	s_nop 0
	global_load_lds_dwordx4 v[220:221], off
	s_waitcnt vmcnt(8)
	s_waitcnt lgkmcnt(0)
	s_barrier
; #define PG8_STAGE(bufoff, gbase, voff) do { _Pragma("unroll") for (int _i = 0; _i < 2; ++_i) \
;         __builtin_amdgcn_global_load_lds((const unsigned*)((const char*)(gbase) + (voff)[_i]), (PG8_LAS unsigned*)(lds + (bufoff) + ldsw + _i * 8192), 16, 0, 0); } while (0)
; #define PG8_LDA(dst, b, h) do { _Pragma("unroll") for (int m = 0; m < 4; ++m) _Pragma("unroll") for (int k = 0; k < 2; ++k) dst[m][k] = *(const PG8_LAS bf16x8*)(lds + PG8_SA(b, h) + aoff + m * 2048 + k * 1024); } while (0)
; #define PG8_LDB(dst, b, h) do { _Pragma("unroll") for (int n = 0; n < 2; ++n) _Pragma("unroll") for (int k = 0; k < 2; ++k) dst[n][k] = *(const PG8_LAS bf16x8*)(lds + PG8_SB(b, h) + boff + n * 2048 + k * 1024); } while (0)
; #define PG8_MMA(ai, bj, At, Bt) do { __builtin_amdgcn_s_setprio(1); _Pragma("unroll") for (int m = 0; m < 4; ++m) _Pragma("unroll") for (int n = 0; n < 2; ++n) _Pragma("unroll") for (int k = 0; k < 2; ++k) \
;         acc[ai][bj][m][n] = __builtin_amdgcn_mfma_f32_16x16x32_bf16(Bt[n][k], At[m][k], acc[ai][bj][m][n], 0, 0, 0); __builtin_amdgcn_s_setprio(0); } while (0)
; #define PG8_WAIT_V(n) asm volatile("s_waitcnt vmcnt(" #n ")" ::: "memory")
; #define PG8_WAIT_L(n) asm volatile("s_waitcnt lgkmcnt(" #n ")" ::: "memory")
; #define PG8_BAR __builtin_amdgcn_s_barrier()
; #define PG8_SCHED __builtin_amdgcn_sched_barrier(0)
;     ...
;             PG8_WAIT_V(8); PG8_WAIT_L(0); PG8_BAR; PG8_MMA(1, 0, At, B0); PG8_MMA(1, 1, At, B1); PG8_BAR; PG8_SCHED;
;             PG8_LDB(B0, 1, 0); PG8_LDB(B1, 1, 1); PG8_SCHED; PG8_LDA(At, 1, 0); PG8_STAGE(PG8_SA(0, 1), a2 + hstepA, voffA);
;             PG8_WAIT_V(8); PG8_WAIT_L(0); PG8_BAR; PG8_MMA(0, 0, At, B0); PG8_MMA(0, 1, At, B1); PG8_BAR; PG8_SCHED;
	s_setprio 1
	s_waitcnt lgkmcnt(0)
	v_mfma_f32_16x16x32_bf16 v[68:71], v[72:75], v[168:171], v[68:71]
	v_mfma_f32_16x16x32_bf16 v[68:71], v[76:79], v[172:175], v[68:71]
	v_mfma_f32_16x16x32_bf16 v[64:67], v[88:91], v[172:175], v[64:67]
	v_mfma_f32_16x16x32_bf16 v[64:67], v[80:83], v[168:171], v[64:67]
	v_mfma_f32_16x16x32_bf16 v[48:51], v[80:83], v[176:179], v[48:51]
	v_mfma_f32_16x16x32_bf16 v[48:51], v[88:91], v[200:203], v[48:51]
	v_mfma_f32_16x16x32_bf16 v[52:55], v[76:79], v[200:203], v[52:55]
	v_mfma_f32_16x16x32_bf16 v[52:55], v[72:75], v[176:179], v[52:55]
	v_mfma_f32_16x16x32_bf16 v[34:37], v[72:75], v[204:207], v[36:39]
	v_mfma_f32_16x16x32_bf16 v[34:37], v[76:79], v[208:211], v[34:37]
	v_mfma_f32_16x16x32_bf16 v[26:29], v[88:91], v[208:211], v[26:29]
	v_mfma_f32_16x16x32_bf16 v[26:29], v[80:83], v[204:207], v[26:29]
	v_mfma_f32_16x16x32_bf16 v[10:13], v[80:83], v[212:215], v[10:13]
	v_mfma_f32_16x16x32_bf16 v[10:13], v[88:91], v[216:219], v[10:13]
	v_mfma_f32_16x16x32_bf16 v[14:17], v[76:79], v[216:219], v[14:17]
	v_mfma_f32_16x16x32_bf16 v[14:17], v[72:75], v[212:215], v[14:17]
	s_setprio 0
	s_setprio 1
	v_mfma_f32_16x16x32_bf16 v[60:63], v[152:155], v[168:171], v[60:63]
	v_mfma_f32_16x16x32_bf16 v[60:63], v[156:159], v[172:175], v[60:63]
	v_mfma_f32_16x16x32_bf16 v[56:59], v[164:167], v[172:175], v[56:59]
	v_mfma_f32_16x16x32_bf16 v[56:59], v[160:163], v[168:171], v[56:59]
	v_mfma_f32_16x16x32_bf16 v[38:41], v[160:163], v[176:179], v[40:43]
	v_mfma_f32_16x16x32_bf16 v[40:43], v[164:167], v[200:203], v[38:41]
	v_mfma_f32_16x16x32_bf16 v[44:47], v[156:159], v[200:203], v[44:47]
	v_mfma_f32_16x16x32_bf16 v[44:47], v[152:155], v[176:179], v[44:47]
	v_mfma_f32_16x16x32_bf16 v[22:25], v[152:155], v[204:207], v[22:25]
	v_mfma_f32_16x16x32_bf16 v[22:25], v[156:159], v[208:211], v[22:25]
	v_mfma_f32_16x16x32_bf16 v[18:21], v[164:167], v[208:211], v[18:21]
	v_mfma_f32_16x16x32_bf16 v[18:21], v[160:163], v[204:207], v[18:21]
	v_mfma_f32_16x16x32_bf16 v[2:5], v[160:163], v[212:215], v[2:5]
	v_mfma_f32_16x16x32_bf16 v[2:5], v[164:167], v[216:219], v[2:5]
	v_mfma_f32_16x16x32_bf16 v[6:9], v[156:159], v[216:219], v[6:9]
	v_mfma_f32_16x16x32_bf16 v[6:9], v[152:155], v[212:215], v[6:9]
	s_setprio 0
	s_barrier
	s_add_i32 s23, 0, 0x18000
	v_add_u32_e32 v32, s23, v239
	s_add_i32 s25, 0, 0x1c000
	ds_read_b128 v[72:75], v32
	ds_read_b128 v[76:79], v32 offset:1024
	ds_read_b128 v[80:83], v32 offset:2048
	ds_read_b128 v[88:91], v32 offset:3072
	v_add_u32_e32 v32, s25, v239
	ds_read_b128 v[152:155], v32
	ds_read_b128 v[156:159], v32 offset:1024
	ds_read_b128 v[160:163], v32 offset:2048
	ds_read_b128 v[164:167], v32 offset:3072
	s_add_u32 s28, s92, 0x80000
	s_addc_u32 s29, s93, 0
	s_mov_b32 m0, s74
	v_lshl_add_u64 v[38:39], s[28:29], 0, v[30:31]
	ds_read_b128 v[168:171], v251 offset:32768
	ds_read_b128 v[172:175], v251 offset:33792
	ds_read_b128 v[176:179], v251 offset:34816
	ds_read_b128 v[200:203], v251 offset:35840
	ds_read_b128 v[204:207], v251 offset:36864
	ds_read_b128 v[208:211], v251 offset:37888
	ds_read_b128 v[212:215], v251 offset:38912
	ds_read_b128 v[216:219], v251 offset:39936
	global_load_lds_dwordx4 v[38:39], off
	v_lshl_add_u64 v[38:39], s[28:29], 0, v[180:181]
	s_mov_b32 m0, s96
	s_nop 0
	global_load_lds_dwordx4 v[38:39], off
	s_waitcnt vmcnt(8)
	s_waitcnt lgkmcnt(0)
	s_barrier
	s_setprio 1
	s_waitcnt lgkmcnt(0)
	v_mfma_f32_16x16x32_bf16 v[84:87], v[72:75], v[168:171], v[84:87]
	v_mfma_f32_16x16x32_bf16 v[84:87], v[76:79], v[172:175], v[84:87]
	v_mfma_f32_16x16x32_bf16 v[148:151], v[88:91], v[172:175], v[148:151]
	v_mfma_f32_16x16x32_bf16 v[148:151], v[80:83], v[168:171], v[148:151]
	v_mfma_f32_16x16x32_bf16 v[132:135], v[80:83], v[176:179], v[132:135]
	v_mfma_f32_16x16x32_bf16 v[132:135], v[88:91], v[200:203], v[132:135]
	v_mfma_f32_16x16x32_bf16 v[136:139], v[76:79], v[200:203], v[136:139]
	v_mfma_f32_16x16x32_bf16 v[136:139], v[72:75], v[176:179], v[136:139]
	v_mfma_f32_16x16x32_bf16 v[120:123], v[72:75], v[204:207], v[120:123]
	v_mfma_f32_16x16x32_bf16 v[120:123], v[76:79], v[208:211], v[120:123]
	v_mfma_f32_16x16x32_bf16 v[116:119], v[88:91], v[208:211], v[116:119]
	v_mfma_f32_16x16x32_bf16 v[116:119], v[80:83], v[204:207], v[116:119]
	v_mfma_f32_16x16x32_bf16 v[100:103], v[80:83], v[212:215], v[100:103]
	v_mfma_f32_16x16x32_bf16 v[100:103], v[88:91], v[216:219], v[100:103]
	v_mfma_f32_16x16x32_bf16 v[104:107], v[76:79], v[216:219], v[104:107]
	v_mfma_f32_16x16x32_bf16 v[104:107], v[72:75], v[212:215], v[104:107]
	s_setprio 0
	s_setprio 1
	v_mfma_f32_16x16x32_bf16 v[144:147], v[152:155], v[168:171], v[144:147]
	v_mfma_f32_16x16x32_bf16 v[144:147], v[156:159], v[172:175], v[144:147]
	v_mfma_f32_16x16x32_bf16 v[140:143], v[164:167], v[172:175], v[140:143]
	v_mfma_f32_16x16x32_bf16 v[140:143], v[160:163], v[168:171], v[140:143]
	v_mfma_f32_16x16x32_bf16 v[124:127], v[160:163], v[176:179], v[124:127]
	v_mfma_f32_16x16x32_bf16 v[124:127], v[164:167], v[200:203], v[124:127]
	v_mfma_f32_16x16x32_bf16 v[128:131], v[156:159], v[200:203], v[128:131]
	v_mfma_f32_16x16x32_bf16 v[128:131], v[152:155], v[176:179], v[128:131]
	v_mfma_f32_16x16x32_bf16 v[112:115], v[152:155], v[204:207], v[112:115]
	v_mfma_f32_16x16x32_bf16 v[112:115], v[156:159], v[208:211], v[112:115]
	v_mfma_f32_16x16x32_bf16 v[108:111], v[164:167], v[208:211], v[108:111]
	v_mfma_f32_16x16x32_bf16 v[108:111], v[160:163], v[204:207], v[108:111]
	v_mfma_f32_16x16x32_bf16 v[92:95], v[160:163], v[212:215], v[92:95]
	v_mfma_f32_16x16x32_bf16 v[92:95], v[164:167], v[216:219], v[92:95]
	v_mfma_f32_16x16x32_bf16 v[96:99], v[156:159], v[216:219], v[96:99]
	v_mfma_f32_16x16x32_bf16 v[96:99], v[152:155], v[212:215], v[96:99]
	s_setprio 0
	s_barrier
; #define PG8_STAGE(bufoff, gbase, voff) do { _Pragma("unroll") for (int _i = 0; _i < 2; ++_i) \
;         __builtin_amdgcn_global_load_lds((const unsigned*)((const char*)(gbase) + (voff)[_i]), (PG8_LAS unsigned*)(lds + (bufoff) + ldsw + _i * 8192), 16, 0, 0); } while (0)
; #define PG8_LDA(dst, b, h) do { _Pragma("unroll") for (int m = 0; m < 4; ++m) _Pragma("unroll") for (int k = 0; k < 2; ++k) dst[m][k] = *(const PG8_LAS bf16x8*)(lds + PG8_SA(b, h) + aoff + m * 2048 + k * 1024); } while (0)
; #define PG8_MMA(ai, bj, At, Bt) do { __builtin_amdgcn_s_setprio(1); _Pragma("unroll") for (int m = 0; m < 4; ++m) _Pragma("unroll") for (int n = 0; n < 2; ++n) _Pragma("unroll") for (int k = 0; k < 2; ++k) \
;         acc[ai][bj][m][n] = __builtin_amdgcn_mfma_f32_16x16x32_bf16(Bt[n][k], At[m][k], acc[ai][bj][m][n], 0, 0, 0); __builtin_amdgcn_s_setprio(0); } while (0)
; #define PG8_WAIT_V(n) asm volatile("s_waitcnt vmcnt(" #n ")" ::: "memory")
; #define PG8_WAIT_L(n) asm volatile("s_waitcnt lgkmcnt(" #n ")" ::: "memory")
; #define PG8_BAR __builtin_amdgcn_s_barrier()
; #define PG8_SCHED __builtin_amdgcn_sched_barrier(0)
;     ...
;             PG8_LDA(At, 1, 1); PG8_STAGE(PG8_SB(1, 0), b3, voffB); PG8_STAGE(PG8_SB(1, 1), b3 + hstep, voffB); PG8_STAGE(PG8_SA(1, 0), a3, voffA);
;             PG8_WAIT_V(8); PG8_WAIT_L(0); PG8_BAR; PG8_MMA(1, 0, At, B0); PG8_MMA(1, 1, At, B1); PG8_BAR; PG8_SCHED;
;     ...
;         if constexpr (ALIGN_EPI) { if (wr == 0) PG8_BAR; }
	s_add_i32 s23, s23, s3
	v_lshl_add_u64 v[38:39], v[186:187], 0, s[64:65]
	s_mov_b32 m0, s23
	ds_read_b128 v[168:171], v251 offset:49152
	ds_read_b128 v[172:175], v251 offset:50176
	ds_read_b128 v[176:179], v251 offset:51200
	ds_read_b128 v[200:203], v251 offset:52224
	ds_read_b128 v[204:207], v251 offset:53248
	ds_read_b128 v[208:211], v251 offset:54272
	ds_read_b128 v[212:215], v251 offset:55296
	ds_read_b128 v[216:219], v251 offset:56320
	global_load_lds_dwordx4 v[38:39], off
	s_add_i32 m0, s23, 0x2000
	s_add_u32 s28, s38, 0x80080
	v_lshl_add_u64 v[38:39], v[188:189], 0, s[64:65]
	s_addc_u32 s29, s39, 0
	s_add_i32 s23, s25, s3
	global_load_lds_dwordx4 v[38:39], off
	v_lshl_add_u64 v[38:39], s[28:29], 0, v[30:31]
	s_mov_b32 m0, s23
	s_nop 0
	global_load_lds_dwordx4 v[38:39], off
	v_lshl_add_u64 v[38:39], s[28:29], 0, v[180:181]
	s_add_i32 m0, s23, 0x2000
	s_nop 0
	global_load_lds_dwordx4 v[38:39], off
	v_lshl_add_u64 v[38:39], v[190:191], 0, s[64:65]
	s_mov_b32 m0, s53
	s_nop 0
	global_load_lds_dwordx4 v[38:39], off
	v_lshl_add_u64 v[38:39], v[220:221], 0, s[64:65]
	s_mov_b32 m0, s4
	s_nop 0
	global_load_lds_dwordx4 v[38:39], off
	s_waitcnt vmcnt(8)
	s_waitcnt lgkmcnt(0)
	s_barrier
	s_setprio 1
	s_waitcnt lgkmcnt(0)
	v_mfma_f32_16x16x32_bf16 v[68:71], v[72:75], v[168:171], v[68:71]
	v_mfma_f32_16x16x32_bf16 v[68:71], v[76:79], v[172:175], v[68:71]
	v_mfma_f32_16x16x32_bf16 v[64:67], v[88:91], v[172:175], v[64:67]
	v_mfma_f32_16x16x32_bf16 v[64:67], v[80:83], v[168:171], v[64:67]
	v_mfma_f32_16x16x32_bf16 v[48:51], v[80:83], v[176:179], v[48:51]
	v_mfma_f32_16x16x32_bf16 v[48:51], v[88:91], v[200:203], v[48:51]
	v_mfma_f32_16x16x32_bf16 v[52:55], v[76:79], v[200:203], v[52:55]
	v_mfma_f32_16x16x32_bf16 v[52:55], v[72:75], v[176:179], v[52:55]
	v_mfma_f32_16x16x32_bf16 v[34:37], v[72:75], v[204:207], v[34:37]
	v_mfma_f32_16x16x32_bf16 v[36:39], v[76:79], v[208:211], v[34:37]
	v_mfma_f32_16x16x32_bf16 v[26:29], v[88:91], v[208:211], v[26:29]
	v_mfma_f32_16x16x32_bf16 v[26:29], v[80:83], v[204:207], v[26:29]
	v_mfma_f32_16x16x32_bf16 v[10:13], v[80:83], v[212:215], v[10:13]
	v_mfma_f32_16x16x32_bf16 v[10:13], v[88:91], v[216:219], v[10:13]
	v_mfma_f32_16x16x32_bf16 v[14:17], v[76:79], v[216:219], v[14:17]
	v_mfma_f32_16x16x32_bf16 v[14:17], v[72:75], v[212:215], v[14:17]
	s_setprio 0
	s_setprio 1
	v_mfma_f32_16x16x32_bf16 v[60:63], v[152:155], v[168:171], v[60:63]
	v_mfma_f32_16x16x32_bf16 v[60:63], v[156:159], v[172:175], v[60:63]
	v_mfma_f32_16x16x32_bf16 v[56:59], v[164:167], v[172:175], v[56:59]
	v_mfma_f32_16x16x32_bf16 v[56:59], v[160:163], v[168:171], v[56:59]
	v_mfma_f32_16x16x32_bf16 v[40:43], v[160:163], v[176:179], v[40:43]
	v_mfma_f32_16x16x32_bf16 v[40:43], v[164:167], v[200:203], v[40:43]
	v_mfma_f32_16x16x32_bf16 v[44:47], v[156:159], v[200:203], v[44:47]
	v_mfma_f32_16x16x32_bf16 v[44:47], v[152:155], v[176:179], v[44:47]
	v_mfma_f32_16x16x32_bf16 v[22:25], v[152:155], v[204:207], v[22:25]
	v_mfma_f32_16x16x32_bf16 v[22:25], v[156:159], v[208:211], v[22:25]
	v_mfma_f32_16x16x32_bf16 v[18:21], v[164:167], v[208:211], v[18:21]
	v_mfma_f32_16x16x32_bf16 v[18:21], v[160:163], v[204:207], v[18:21]
	v_mfma_f32_16x16x32_bf16 v[2:5], v[160:163], v[212:215], v[2:5]
	v_mfma_f32_16x16x32_bf16 v[2:5], v[164:167], v[216:219], v[2:5]
	v_mfma_f32_16x16x32_bf16 v[6:9], v[156:159], v[216:219], v[6:9]
	v_mfma_f32_16x16x32_bf16 v[6:9], v[152:155], v[212:215], v[6:9]
	s_setprio 0
	s_barrier
	s_add_i32 s23, s19, 2
	s_add_u32 s9, s9, 0x100
	s_addc_u32 s17, s17, 0
	s_cmp_ge_i32 s19, s40
	s_mov_b64 s[28:29], s[30:31]
	s_mov_b32 s19, s23
	s_cbranch_scc0 .LBB0_1064
	s_and_b64 vcc, exec, s[14:15]
	s_cbranch_vccz .LBB0_1067
	s_barrier

; #define PG8_STAGE(bufoff, gbase, voff) do { _Pragma("unroll") for (int _i = 0; _i < 2; ++_i) \
;         __builtin_amdgcn_global_load_lds((const unsigned*)((const char*)(gbase) + (voff)[_i]), (PG8_LAS unsigned*)(lds + (bufoff) + ldsw + _i * 8192), 16, 0, 0); } while (0)
; #define PG8_LDA(dst, b, h) do { _Pragma("unroll") for (int m = 0; m < 4; ++m) _Pragma("unroll") for (int k = 0; k < 2; ++k) dst[m][k] = *(const PG8_LAS bf16x8*)(lds + PG8_SA(b, h) + aoff + m * 2048 + k * 1024); } while (0)
; #define PG8_LDB(dst, b, h) do { _Pragma("unroll") for (int n = 0; n < 2; ++n) _Pragma("unroll") for (int k = 0; k < 2; ++k) dst[n][k] = *(const PG8_LAS bf16x8*)(lds + PG8_SB(b, h) + boff + n * 2048 + k * 1024); } while (0)
; #define PG8_MMA(ai, bj, At, Bt) do { __builtin_amdgcn_s_setprio(1); _Pragma("unroll") for (int m = 0; m < 4; ++m) _Pragma("unroll") for (int n = 0; n < 2; ++n) _Pragma("unroll") for (int k = 0; k < 2; ++k) \
;         acc[ai][bj][m][n] = __builtin_amdgcn_mfma_f32_16x16x32_bf16(Bt[n][k], At[m][k], acc[ai][bj][m][n], 0, 0, 0); __builtin_amdgcn_s_setprio(0); } while (0)
; #define PG8_WAIT_V(n) asm volatile("s_waitcnt vmcnt(" #n ")" ::: "memory")
; #define PG8_WAIT_L(n) asm volatile("s_waitcnt lgkmcnt(" #n ")" ::: "memory")
; #define PG8_BAR __builtin_amdgcn_s_barrier()
; #define PG8_SCHED __builtin_amdgcn_sched_barrier(0)
;     ...
;             const bool last = (t == nt - 2);
;             const char* a1 = cA + (size_t)(t + 1) * kstep;
;             const char* a2 = last ? nA : cA + (size_t)(t + 2) * kstep; const char* b2 = last ? nB : cB + (size_t)(t + 2) * kstep;
;             const char* a3 = a2 + kstep; const char* b3 = b2 + kstep;
;             if (last && has_next) S.a_ready(nxt);
;             if constexpr (SP2) {
;             PG8_LDB(B0, 0, 0); PG8_LDB(B1, 0, 1); PG8_SCHED; PG8_LDA(At, 0, 0); PG8_STAGE(PG8_SA(1, 1), a1 + hstepA, voffA);
;             PG8_WAIT_V(8); PG8_WAIT_L(0); PG8_BAR; PG8_MMA(0, 0, At, B0); PG8_MMA(0, 1, At, B1); PG8_BAR; PG8_SCHED;
;             PG8_LDA(At, 0, 1); PG8_STAGE(PG8_SB(0, 0), b2, voffB); PG8_STAGE(PG8_SB(0, 1), b2 + hstep, voffB); PG8_STAGE(PG8_SA(0, 0), a2, voffA);
;             PG8_WAIT_V(8); PG8_WAIT_L(0); PG8_BAR; PG8_MMA(1, 0, At, B0); PG8_MMA(1, 1, At, B1); PG8_BAR; PG8_SCHED;
.LBB0_1332:
	s_add_u32 s26, s24, 0xfff80080
	s_addc_u32 s27, s25, -1
	s_add_i32 s42, 0, 0x10000
	s_cmp_eq_u32 s79, 28
	s_cselect_b32 s29, s11, s27
	s_cselect_b32 s28, s48, s26
	s_cselect_b32 s27, s9, s78
	s_cselect_b32 s26, s33, s74
	s_add_i32 s46, 0, 0x14000
	v_add_u32_e32 v106, s42, v31
	v_add_u32_e32 v174, s46, v31
	ds_read_b128 v[94:97], v106
	ds_read_b128 v[98:101], v106 offset:1024
	ds_read_b128 v[102:105], v106 offset:2048
	ds_read_b128 v[106:109], v106 offset:3072
	ds_read_b128 v[160:163], v174
	ds_read_b128 v[164:167], v174 offset:1024
	ds_read_b128 v[170:173], v174 offset:2048
	ds_read_b128 v[174:177], v174 offset:3072
	v_lshl_add_u64 v[182:183], s[24:25], 0, v[156:157]
	s_add_i32 m0, s19, 0xc000
	ds_read_b128 v[178:181], v169
	ds_read_b128 v[186:189], v169 offset:1024
	ds_read_b128 v[196:199], v169 offset:2048
	ds_read_b128 v[200:203], v169 offset:3072
	ds_read_b128 v[204:207], v169 offset:4096
	ds_read_b128 v[208:211], v169 offset:5120
	ds_read_b128 v[212:215], v169 offset:6144
	ds_read_b128 v[216:219], v169 offset:7168
	global_load_lds_dwordx4 v[182:183], off
	v_lshl_add_u64 v[182:183], s[24:25], 0, v[158:159]
	s_add_i32 m0, s19, 0xe000
	s_nop 0
	global_load_lds_dwordx4 v[182:183], off
	s_waitcnt vmcnt(8)
	s_waitcnt lgkmcnt(0)
	s_barrier
	s_setprio 1
	s_waitcnt lgkmcnt(0)
	v_mfma_f32_16x16x32_bf16 v[146:149], v[94:97], v[178:181], v[146:149]
	v_mfma_f32_16x16x32_bf16 v[146:149], v[98:101], v[186:189], v[146:149]
	v_mfma_f32_16x16x32_bf16 v[142:145], v[106:109], v[186:189], v[142:145]
	v_mfma_f32_16x16x32_bf16 v[142:145], v[102:105], v[178:181], v[142:145]
	v_mfma_f32_16x16x32_bf16 v[126:129], v[102:105], v[196:199], v[126:129]
	v_mfma_f32_16x16x32_bf16 v[126:129], v[106:109], v[200:203], v[126:129]
	v_mfma_f32_16x16x32_bf16 v[130:133], v[98:101], v[200:203], v[130:133]
	v_mfma_f32_16x16x32_bf16 v[130:133], v[94:97], v[196:199], v[130:133]
	v_mfma_f32_16x16x32_bf16 v[114:117], v[94:97], v[204:207], v[114:117]
	v_mfma_f32_16x16x32_bf16 v[114:117], v[98:101], v[208:211], v[114:117]
	v_mfma_f32_16x16x32_bf16 v[110:113], v[106:109], v[208:211], v[110:113]
	v_mfma_f32_16x16x32_bf16 v[110:113], v[102:105], v[204:207], v[110:113]
	v_mfma_f32_16x16x32_bf16 v[78:81], v[102:105], v[212:215], v[78:81]
	v_mfma_f32_16x16x32_bf16 v[78:81], v[106:109], v[216:219], v[78:81]
	v_mfma_f32_16x16x32_bf16 v[82:85], v[98:101], v[216:219], v[82:85]
	v_mfma_f32_16x16x32_bf16 v[82:85], v[94:97], v[212:215], v[82:85]
	s_setprio 0
	s_setprio 1
	v_mfma_f32_16x16x32_bf16 v[138:141], v[160:163], v[178:181], v[138:141]
	v_mfma_f32_16x16x32_bf16 v[138:141], v[164:167], v[186:189], v[138:141]
	v_mfma_f32_16x16x32_bf16 v[134:137], v[174:177], v[186:189], v[134:137]
	v_mfma_f32_16x16x32_bf16 v[134:137], v[170:173], v[178:181], v[134:137]
	v_mfma_f32_16x16x32_bf16 v[118:121], v[170:173], v[196:199], v[118:121]
	v_mfma_f32_16x16x32_bf16 v[118:121], v[174:177], v[200:203], v[118:121]
	v_mfma_f32_16x16x32_bf16 v[122:125], v[164:167], v[200:203], v[122:125]
	v_mfma_f32_16x16x32_bf16 v[122:125], v[160:163], v[196:199], v[122:125]
	v_mfma_f32_16x16x32_bf16 v[90:93], v[160:163], v[204:207], v[90:93]
	v_mfma_f32_16x16x32_bf16 v[90:93], v[164:167], v[208:211], v[90:93]
	v_mfma_f32_16x16x32_bf16 v[86:89], v[174:177], v[208:211], v[86:89]
	v_mfma_f32_16x16x32_bf16 v[86:89], v[170:173], v[204:207], v[86:89]
	v_mfma_f32_16x16x32_bf16 v[70:73], v[170:173], v[212:215], v[70:73]
	v_mfma_f32_16x16x32_bf16 v[70:73], v[174:177], v[216:219], v[70:73]
	v_mfma_f32_16x16x32_bf16 v[74:77], v[164:167], v[216:219], v[74:77]
	v_mfma_f32_16x16x32_bf16 v[74:77], v[160:163], v[212:215], v[74:77]
	s_setprio 0
	s_barrier
	s_add_i32 s42, s42, s30
	v_lshl_add_u64 v[182:183], s[26:27], 0, v[32:33]
	s_mov_b32 m0, s42
	ds_read_b128 v[178:181], v169 offset:16384
	ds_read_b128 v[186:189], v169 offset:17408
	ds_read_b128 v[196:199], v169 offset:18432
	ds_read_b128 v[200:203], v169 offset:19456
	ds_read_b128 v[204:207], v169 offset:20480
	ds_read_b128 v[208:211], v169 offset:21504
	ds_read_b128 v[212:215], v169 offset:22528
	ds_read_b128 v[216:219], v169 offset:23552
	global_load_lds_dwordx4 v[182:183], off
	s_add_i32 m0, s42, 0x2000
	s_add_u32 s42, s26, 0x80000
	v_lshl_add_u64 v[190:191], s[26:27], 0, v[154:155]
	s_addc_u32 s43, s27, 0
	s_add_i32 s46, s46, s30
	global_load_lds_dwordx4 v[190:191], off
	v_lshl_add_u64 v[220:221], s[42:43], 0, v[32:33]
	s_mov_b32 m0, s46
	v_lshl_add_u64 v[222:223], s[28:29], 0, v[152:153]
	global_load_lds_dwordx4 v[220:221], off
	v_lshl_add_u64 v[220:221], s[42:43], 0, v[154:155]
	s_add_i32 m0, s46, 0x2000
	s_nop 0
	global_load_lds_dwordx4 v[220:221], off
	v_lshl_add_u64 v[220:221], s[28:29], 0, v[150:151]
	s_mov_b32 m0, s19
	s_nop 0
	global_load_lds_dwordx4 v[220:221], off
	s_mov_b32 m0, s23
	s_nop 0
	global_load_lds_dwordx4 v[222:223], off
	s_waitcnt vmcnt(8)
	s_waitcnt lgkmcnt(0)
	s_barrier
; #define PG8_STAGE(bufoff, gbase, voff) do { _Pragma("unroll") for (int _i = 0; _i < 2; ++_i) \
;         __builtin_amdgcn_global_load_lds((const unsigned*)((const char*)(gbase) + (voff)[_i]), (PG8_LAS unsigned*)(lds + (bufoff) + ldsw + _i * 8192), 16, 0, 0); } while (0)
; #define PG8_LDA(dst, b, h) do { _Pragma("unroll") for (int m = 0; m < 4; ++m) _Pragma("unroll") for (int k = 0; k < 2; ++k) dst[m][k] = *(const PG8_LAS bf16x8*)(lds + PG8_SA(b, h) + aoff + m * 2048 + k * 1024); } while (0)
; #define PG8_LDB(dst, b, h) do { _Pragma("unroll") for (int n = 0; n < 2; ++n) _Pragma("unroll") for (int k = 0; k < 2; ++k) dst[n][k] = *(const PG8_LAS bf16x8*)(lds + PG8_SB(b, h) + boff + n * 2048 + k * 1024); } while (0)
; #define PG8_MMA(ai, bj, At, Bt) do { __builtin_amdgcn_s_setprio(1); _Pragma("unroll") for (int m = 0; m < 4; ++m) _Pragma("unroll") for (int n = 0; n < 2; ++n) _Pragma("unroll") for (int k = 0; k < 2; ++k) \
;         acc[ai][bj][m][n] = __builtin_amdgcn_mfma_f32_16x16x32_bf16(Bt[n][k], At[m][k], acc[ai][bj][m][n], 0, 0, 0); __builtin_amdgcn_s_setprio(0); } while (0)
; #define PG8_WAIT_V(n) asm volatile("s_waitcnt vmcnt(" #n ")" ::: "memory")
; #define PG8_WAIT_L(n) asm volatile("s_waitcnt lgkmcnt(" #n ")" ::: "memory")
; #define PG8_BAR __builtin_amdgcn_s_barrier()
; #define PG8_SCHED __builtin_amdgcn_sched_barrier(0)
;     ...
;             PG8_WAIT_V(8); PG8_WAIT_L(0); PG8_BAR; PG8_MMA(1, 0, At, B0); PG8_MMA(1, 1, At, B1); PG8_BAR; PG8_SCHED;
;             PG8_LDB(B0, 1, 0); PG8_LDB(B1, 1, 1); PG8_SCHED; PG8_LDA(At, 1, 0); PG8_STAGE(PG8_SA(0, 1), a2 + hstepA, voffA);
;             PG8_WAIT_V(8); PG8_WAIT_L(0); PG8_BAR; PG8_MMA(0, 0, At, B0); PG8_MMA(0, 1, At, B1); PG8_BAR; PG8_SCHED;
	s_setprio 1
	s_waitcnt lgkmcnt(0)
	v_mfma_f32_16x16x32_bf16 v[66:69], v[94:97], v[178:181], v[66:69]
	v_mfma_f32_16x16x32_bf16 v[66:69], v[98:101], v[186:189], v[66:69]
	v_mfma_f32_16x16x32_bf16 v[62:65], v[106:109], v[186:189], v[62:65]
	v_mfma_f32_16x16x32_bf16 v[62:65], v[102:105], v[178:181], v[62:65]
	v_mfma_f32_16x16x32_bf16 v[46:49], v[102:105], v[196:199], v[46:49]
	v_mfma_f32_16x16x32_bf16 v[46:49], v[106:109], v[200:203], v[46:49]
	v_mfma_f32_16x16x32_bf16 v[50:53], v[98:101], v[200:203], v[50:53]
	v_mfma_f32_16x16x32_bf16 v[50:53], v[94:97], v[196:199], v[50:53]
	v_mfma_f32_16x16x32_bf16 v[34:37], v[94:97], v[204:207], v[34:37]
	v_mfma_f32_16x16x32_bf16 v[34:37], v[98:101], v[208:211], v[34:37]
	v_mfma_f32_16x16x32_bf16 v[26:29], v[106:109], v[208:211], v[26:29]
	v_mfma_f32_16x16x32_bf16 v[26:29], v[102:105], v[204:207], v[26:29]
	v_mfma_f32_16x16x32_bf16 v[10:13], v[102:105], v[212:215], v[10:13]
	v_mfma_f32_16x16x32_bf16 v[10:13], v[106:109], v[216:219], v[10:13]
	v_mfma_f32_16x16x32_bf16 v[14:17], v[98:101], v[216:219], v[14:17]
	v_mfma_f32_16x16x32_bf16 v[14:17], v[94:97], v[212:215], v[14:17]
	s_setprio 0
	s_setprio 1
	v_mfma_f32_16x16x32_bf16 v[58:61], v[160:163], v[178:181], v[58:61]
	v_mfma_f32_16x16x32_bf16 v[58:61], v[164:167], v[186:189], v[58:61]
	v_mfma_f32_16x16x32_bf16 v[54:57], v[174:177], v[186:189], v[54:57]
	v_mfma_f32_16x16x32_bf16 v[54:57], v[170:173], v[178:181], v[54:57]
	v_mfma_f32_16x16x32_bf16 v[38:41], v[170:173], v[196:199], v[38:41]
	v_mfma_f32_16x16x32_bf16 v[38:41], v[174:177], v[200:203], v[38:41]
	v_mfma_f32_16x16x32_bf16 v[42:45], v[164:167], v[200:203], v[42:45]
	v_mfma_f32_16x16x32_bf16 v[42:45], v[160:163], v[196:199], v[42:45]
	v_mfma_f32_16x16x32_bf16 v[22:25], v[160:163], v[204:207], v[22:25]
	v_mfma_f32_16x16x32_bf16 v[22:25], v[164:167], v[208:211], v[22:25]
	v_mfma_f32_16x16x32_bf16 v[18:21], v[174:177], v[208:211], v[18:21]
	v_mfma_f32_16x16x32_bf16 v[18:21], v[170:173], v[204:207], v[18:21]
	v_mfma_f32_16x16x32_bf16 v[2:5], v[170:173], v[212:215], v[2:5]
	v_mfma_f32_16x16x32_bf16 v[2:5], v[174:177], v[216:219], v[2:5]
	v_mfma_f32_16x16x32_bf16 v[6:9], v[164:167], v[216:219], v[6:9]
	v_mfma_f32_16x16x32_bf16 v[6:9], v[160:163], v[212:215], v[6:9]
	s_setprio 0
	s_barrier
	s_add_i32 s42, 0, 0x18000
	s_add_i32 s43, 0, 0x1c000
	v_add_u32_e32 v106, s42, v31
	v_add_u32_e32 v174, s43, v31
	ds_read_b128 v[94:97], v106
	ds_read_b128 v[98:101], v106 offset:1024
	ds_read_b128 v[102:105], v106 offset:2048
	ds_read_b128 v[106:109], v106 offset:3072
	ds_read_b128 v[160:163], v174
	ds_read_b128 v[164:167], v174 offset:1024
	ds_read_b128 v[170:173], v174 offset:2048
	ds_read_b128 v[174:177], v174 offset:3072
	s_add_u32 s28, s28, 0x80000
	s_addc_u32 s29, s29, 0
	s_mov_b32 m0, s31
	v_lshl_add_u64 v[224:225], s[28:29], 0, v[150:151]
	ds_read_b128 v[178:181], v169 offset:32768
	ds_read_b128 v[186:189], v169 offset:33792
	ds_read_b128 v[196:199], v169 offset:34816
	ds_read_b128 v[200:203], v169 offset:35840
	ds_read_b128 v[204:207], v169 offset:36864
	ds_read_b128 v[208:211], v169 offset:37888
	ds_read_b128 v[212:215], v169 offset:38912
	ds_read_b128 v[216:219], v169 offset:39936
	global_load_lds_dwordx4 v[224:225], off
	v_lshl_add_u64 v[224:225], s[28:29], 0, v[152:153]
	s_mov_b32 m0, s38
	s_nop 0
	global_load_lds_dwordx4 v[224:225], off
	s_waitcnt vmcnt(8)
	s_waitcnt lgkmcnt(0)
	s_barrier
	s_setprio 1
	s_waitcnt lgkmcnt(0)
	v_mfma_f32_16x16x32_bf16 v[146:149], v[94:97], v[178:181], v[146:149]
	v_mfma_f32_16x16x32_bf16 v[146:149], v[98:101], v[186:189], v[146:149]
	v_mfma_f32_16x16x32_bf16 v[142:145], v[106:109], v[186:189], v[142:145]
	v_mfma_f32_16x16x32_bf16 v[142:145], v[102:105], v[178:181], v[142:145]
	v_mfma_f32_16x16x32_bf16 v[126:129], v[102:105], v[196:199], v[126:129]
	v_mfma_f32_16x16x32_bf16 v[126:129], v[106:109], v[200:203], v[126:129]
	v_mfma_f32_16x16x32_bf16 v[130:133], v[98:101], v[200:203], v[130:133]
	v_mfma_f32_16x16x32_bf16 v[130:133], v[94:97], v[196:199], v[130:133]
	v_mfma_f32_16x16x32_bf16 v[114:117], v[94:97], v[204:207], v[114:117]
	v_mfma_f32_16x16x32_bf16 v[114:117], v[98:101], v[208:211], v[114:117]
	v_mfma_f32_16x16x32_bf16 v[110:113], v[106:109], v[208:211], v[110:113]
	v_mfma_f32_16x16x32_bf16 v[110:113], v[102:105], v[204:207], v[110:113]
	v_mfma_f32_16x16x32_bf16 v[78:81], v[102:105], v[212:215], v[78:81]
	v_mfma_f32_16x16x32_bf16 v[78:81], v[106:109], v[216:219], v[78:81]
	v_mfma_f32_16x16x32_bf16 v[82:85], v[98:101], v[216:219], v[82:85]
	v_mfma_f32_16x16x32_bf16 v[82:85], v[94:97], v[212:215], v[82:85]
	s_setprio 0
	s_setprio 1
	v_mfma_f32_16x16x32_bf16 v[138:141], v[160:163], v[178:181], v[138:141]
	v_mfma_f32_16x16x32_bf16 v[138:141], v[164:167], v[186:189], v[138:141]
	v_mfma_f32_16x16x32_bf16 v[134:137], v[174:177], v[186:189], v[134:137]
	v_mfma_f32_16x16x32_bf16 v[134:137], v[170:173], v[178:181], v[134:137]
	v_mfma_f32_16x16x32_bf16 v[118:121], v[170:173], v[196:199], v[118:121]
	v_mfma_f32_16x16x32_bf16 v[118:121], v[174:177], v[200:203], v[118:121]
	v_mfma_f32_16x16x32_bf16 v[122:125], v[164:167], v[200:203], v[122:125]
	v_mfma_f32_16x16x32_bf16 v[122:125], v[160:163], v[196:199], v[122:125]
	v_mfma_f32_16x16x32_bf16 v[90:93], v[160:163], v[204:207], v[90:93]
	v_mfma_f32_16x16x32_bf16 v[90:93], v[164:167], v[208:211], v[90:93]
	v_mfma_f32_16x16x32_bf16 v[86:89], v[174:177], v[208:211], v[86:89]
	v_mfma_f32_16x16x32_bf16 v[86:89], v[170:173], v[204:207], v[86:89]
	v_mfma_f32_16x16x32_bf16 v[70:73], v[170:173], v[212:215], v[70:73]
	v_mfma_f32_16x16x32_bf16 v[70:73], v[174:177], v[216:219], v[70:73]
	v_mfma_f32_16x16x32_bf16 v[74:77], v[164:167], v[216:219], v[74:77]
	v_mfma_f32_16x16x32_bf16 v[74:77], v[160:163], v[212:215], v[74:77]
	s_setprio 0
	s_barrier
; #define PG8_STAGE(bufoff, gbase, voff) do { _Pragma("unroll") for (int _i = 0; _i < 2; ++_i) \
;         __builtin_amdgcn_global_load_lds((const unsigned*)((const char*)(gbase) + (voff)[_i]), (PG8_LAS unsigned*)(lds + (bufoff) + ldsw + _i * 8192), 16, 0, 0); } while (0)
; #define PG8_LDA(dst, b, h) do { _Pragma("unroll") for (int m = 0; m < 4; ++m) _Pragma("unroll") for (int k = 0; k < 2; ++k) dst[m][k] = *(const PG8_LAS bf16x8*)(lds + PG8_SA(b, h) + aoff + m * 2048 + k * 1024); } while (0)
; #define PG8_MMA(ai, bj, At, Bt) do { __builtin_amdgcn_s_setprio(1); _Pragma("unroll") for (int m = 0; m < 4; ++m) _Pragma("unroll") for (int n = 0; n < 2; ++n) _Pragma("unroll") for (int k = 0; k < 2; ++k) \
;         acc[ai][bj][m][n] = __builtin_amdgcn_mfma_f32_16x16x32_bf16(Bt[n][k], At[m][k], acc[ai][bj][m][n], 0, 0, 0); __builtin_amdgcn_s_setprio(0); } while (0)
; #define PG8_WAIT_V(n) asm volatile("s_waitcnt vmcnt(" #n ")" ::: "memory")
; #define PG8_WAIT_L(n) asm volatile("s_waitcnt lgkmcnt(" #n ")" ::: "memory")
; #define PG8_BAR __builtin_amdgcn_s_barrier()
; #define PG8_SCHED __builtin_amdgcn_sched_barrier(0)
;     ...
;             PG8_LDA(At, 1, 1); PG8_STAGE(PG8_SB(1, 0), b3, voffB); PG8_STAGE(PG8_SB(1, 1), b3 + hstep, voffB); PG8_STAGE(PG8_SA(1, 0), a3, voffA);
;             PG8_WAIT_V(8); PG8_WAIT_L(0); PG8_BAR; PG8_MMA(1, 0, At, B0); PG8_MMA(1, 1, At, B1); PG8_BAR; PG8_SCHED;
;     ...
;         if constexpr (ALIGN_EPI) { if (wr == 0) PG8_BAR; }
	s_add_i32 s28, s42, s30
	v_lshl_add_u64 v[182:183], v[182:183], 0, s[64:65]
	s_mov_b32 m0, s28
	ds_read_b128 v[178:181], v169 offset:49152
	ds_read_b128 v[186:189], v169 offset:50176
	ds_read_b128 v[196:199], v169 offset:51200
	ds_read_b128 v[200:203], v169 offset:52224
	ds_read_b128 v[204:207], v169 offset:53248
	ds_read_b128 v[208:211], v169 offset:54272
	ds_read_b128 v[212:215], v169 offset:55296
	ds_read_b128 v[216:219], v169 offset:56320
	global_load_lds_dwordx4 v[182:183], off
	s_add_i32 m0, s28, 0x2000
	s_add_u32 s26, s26, 0x80080
	v_lshl_add_u64 v[182:183], v[190:191], 0, s[64:65]
	s_addc_u32 s27, s27, 0
	s_add_i32 s28, s43, s30
	global_load_lds_dwordx4 v[182:183], off
	v_lshl_add_u64 v[182:183], s[26:27], 0, v[32:33]
	s_mov_b32 m0, s28
	s_nop 0
	global_load_lds_dwordx4 v[182:183], off
	v_lshl_add_u64 v[182:183], s[26:27], 0, v[154:155]
	s_add_i32 m0, s28, 0x2000
	s_nop 0
	global_load_lds_dwordx4 v[182:183], off
	v_lshl_add_u64 v[182:183], v[220:221], 0, s[64:65]
	s_mov_b32 m0, s41
	s_nop 0
	global_load_lds_dwordx4 v[182:183], off
	v_lshl_add_u64 v[182:183], v[222:223], 0, s[64:65]
	s_mov_b32 m0, s50
	s_nop 0
	global_load_lds_dwordx4 v[182:183], off
	s_waitcnt vmcnt(8)
	s_waitcnt lgkmcnt(0)
	s_barrier
	s_setprio 1
	s_waitcnt lgkmcnt(0)
	v_mfma_f32_16x16x32_bf16 v[66:69], v[94:97], v[178:181], v[66:69]
	v_mfma_f32_16x16x32_bf16 v[66:69], v[98:101], v[186:189], v[66:69]
	v_mfma_f32_16x16x32_bf16 v[62:65], v[106:109], v[186:189], v[62:65]
	v_mfma_f32_16x16x32_bf16 v[62:65], v[102:105], v[178:181], v[62:65]
	v_mfma_f32_16x16x32_bf16 v[46:49], v[102:105], v[196:199], v[46:49]
	v_mfma_f32_16x16x32_bf16 v[46:49], v[106:109], v[200:203], v[46:49]
	v_mfma_f32_16x16x32_bf16 v[50:53], v[98:101], v[200:203], v[50:53]
	v_mfma_f32_16x16x32_bf16 v[50:53], v[94:97], v[196:199], v[50:53]
	v_mfma_f32_16x16x32_bf16 v[34:37], v[94:97], v[204:207], v[34:37]
	v_mfma_f32_16x16x32_bf16 v[34:37], v[98:101], v[208:211], v[34:37]
	v_mfma_f32_16x16x32_bf16 v[26:29], v[106:109], v[208:211], v[26:29]
	v_mfma_f32_16x16x32_bf16 v[26:29], v[102:105], v[204:207], v[26:29]
	v_mfma_f32_16x16x32_bf16 v[10:13], v[102:105], v[212:215], v[10:13]
	v_mfma_f32_16x16x32_bf16 v[10:13], v[106:109], v[216:219], v[10:13]
	v_mfma_f32_16x16x32_bf16 v[14:17], v[98:101], v[216:219], v[14:17]
	v_mfma_f32_16x16x32_bf16 v[14:17], v[94:97], v[212:215], v[14:17]
	s_setprio 0
	s_setprio 1
	v_mfma_f32_16x16x32_bf16 v[58:61], v[160:163], v[178:181], v[58:61]
	v_mfma_f32_16x16x32_bf16 v[58:61], v[164:167], v[186:189], v[58:61]
	v_mfma_f32_16x16x32_bf16 v[54:57], v[174:177], v[186:189], v[54:57]
	v_mfma_f32_16x16x32_bf16 v[54:57], v[170:173], v[178:181], v[54:57]
	v_mfma_f32_16x16x32_bf16 v[38:41], v[170:173], v[196:199], v[38:41]
	v_mfma_f32_16x16x32_bf16 v[38:41], v[174:177], v[200:203], v[38:41]
	v_mfma_f32_16x16x32_bf16 v[42:45], v[164:167], v[200:203], v[42:45]
	v_mfma_f32_16x16x32_bf16 v[42:45], v[160:163], v[196:199], v[42:45]
	v_mfma_f32_16x16x32_bf16 v[22:25], v[160:163], v[204:207], v[22:25]
	v_mfma_f32_16x16x32_bf16 v[22:25], v[164:167], v[208:211], v[22:25]
	v_mfma_f32_16x16x32_bf16 v[18:21], v[174:177], v[208:211], v[18:21]
	v_mfma_f32_16x16x32_bf16 v[18:21], v[170:173], v[204:207], v[18:21]
	v_mfma_f32_16x16x32_bf16 v[2:5], v[170:173], v[212:215], v[2:5]
	v_mfma_f32_16x16x32_bf16 v[2:5], v[174:177], v[216:219], v[2:5]
	v_mfma_f32_16x16x32_bf16 v[6:9], v[164:167], v[216:219], v[6:9]
	v_mfma_f32_16x16x32_bf16 v[6:9], v[160:163], v[212:215], v[6:9]
	s_setprio 0
	s_barrier
	s_add_i32 s79, s79, 2
	s_add_u32 s24, s24, 0x100
	s_addc_u32 s25, s25, 0
	s_add_u32 s74, s74, 0x100
	s_addc_u32 s78, s78, 0
	s_cmp_gt_u32 s79, 29
	s_cbranch_scc0 .LBB0_1332
	s_and_b64 vcc, exec, s[6:7]
	s_cbranch_vccz .LBB0_1335
	s_barrier

; #define PG8_STAGE(bufoff, gbase, voff) do { _Pragma("unroll") for (int _i = 0; _i < 2; ++_i) \
;         __builtin_amdgcn_global_load_lds((const unsigned*)((const char*)(gbase) + (voff)[_i]), (PG8_LAS unsigned*)(lds + (bufoff) + ldsw + _i * 8192), 16, 0, 0); } while (0)
; #define PG8_LDA(dst, b, h) do { _Pragma("unroll") for (int m = 0; m < 4; ++m) _Pragma("unroll") for (int k = 0; k < 2; ++k) dst[m][k] = *(const PG8_LAS bf16x8*)(lds + PG8_SA(b, h) + aoff + m * 2048 + k * 1024); } while (0)
; #define PG8_LDB(dst, b, h) do { _Pragma("unroll") for (int n = 0; n < 2; ++n) _Pragma("unroll") for (int k = 0; k < 2; ++k) dst[n][k] = *(const PG8_LAS bf16x8*)(lds + PG8_SB(b, h) + boff + n * 2048 + k * 1024); } while (0)
; #define PG8_MMA(ai, bj, At, Bt) do { __builtin_amdgcn_s_setprio(1); _Pragma("unroll") for (int m = 0; m < 4; ++m) _Pragma("unroll") for (int n = 0; n < 2; ++n) _Pragma("unroll") for (int k = 0; k < 2; ++k) \
;         acc[ai][bj][m][n] = __builtin_amdgcn_mfma_f32_16x16x32_bf16(Bt[n][k], At[m][k], acc[ai][bj][m][n], 0, 0, 0); __builtin_amdgcn_s_setprio(0); } while (0)
; #define PG8_WAIT_V(n) asm volatile("s_waitcnt vmcnt(" #n ")" ::: "memory")
; #define PG8_WAIT_L(n) asm volatile("s_waitcnt lgkmcnt(" #n ")" ::: "memory")
; #define PG8_BAR __builtin_amdgcn_s_barrier()
; #define PG8_SCHED __builtin_amdgcn_sched_barrier(0)
;     ...
;             const bool last = (t == nt - 2);
;             const char* a1 = cA + (size_t)(t + 1) * kstep;
;             const char* a2 = last ? nA : cA + (size_t)(t + 2) * kstep; const char* b2 = last ? nB : cB + (size_t)(t + 2) * kstep;
;             const char* a3 = a2 + kstep; const char* b3 = b2 + kstep;
;             if (last && has_next) S.a_ready(nxt);
;             if constexpr (SP2) {
;             PG8_LDB(B0, 0, 0); PG8_LDB(B1, 0, 1); PG8_SCHED; PG8_LDA(At, 0, 0); PG8_STAGE(PG8_SA(1, 1), a1 + hstepA, voffA);
;             PG8_WAIT_V(8); PG8_WAIT_L(0); PG8_BAR; PG8_MMA(0, 0, At, B0); PG8_MMA(0, 1, At, B1); PG8_BAR; PG8_SCHED;
;             PG8_LDA(At, 0, 1); PG8_STAGE(PG8_SB(0, 0), b2, voffB); PG8_STAGE(PG8_SB(0, 1), b2 + hstep, voffB); PG8_STAGE(PG8_SA(0, 0), a2, voffA);
;             PG8_WAIT_V(8); PG8_WAIT_L(0); PG8_BAR; PG8_MMA(1, 0, At, B0); PG8_MMA(1, 1, At, B1); PG8_BAR; PG8_SCHED;
.LBB0_1454:
	s_add_u32 s30, s28, 0x100
	s_addc_u32 s31, s29, 0
	s_add_i32 s27, 0, 0x10000
	s_cmp_eq_u32 s40, s25
	s_cselect_b32 s93, s95, s31
	s_cselect_b32 s92, s94, s30
	v_add_u32_e32 v32, s27, v239
	s_cselect_b32 s39, s97, s23
	s_cselect_b32 s38, s96, s9
	s_add_i32 s33, 0, 0x14000
	ds_read_b128 v[72:75], v32
	ds_read_b128 v[76:79], v32 offset:1024
	ds_read_b128 v[80:83], v32 offset:2048
	ds_read_b128 v[88:91], v32 offset:3072
	v_add_u32_e32 v32, s33, v239
	ds_read_b128 v[152:155], v32
	ds_read_b128 v[156:159], v32 offset:1024
	ds_read_b128 v[160:163], v32 offset:2048
	ds_read_b128 v[164:167], v32 offset:3072
	v_lshl_add_u64 v[34:35], s[28:29], 0, v[196:197]
	s_add_i32 m0, s4, 0xc000
	ds_read_b128 v[168:171], v251
	ds_read_b128 v[172:175], v251 offset:1024
	ds_read_b128 v[176:179], v251 offset:2048
	ds_read_b128 v[186:189], v251 offset:3072
	ds_read_b128 v[200:203], v251 offset:4096
	ds_read_b128 v[204:207], v251 offset:5120
	ds_read_b128 v[208:211], v251 offset:6144
	ds_read_b128 v[212:215], v251 offset:7168
	global_load_lds_dwordx4 v[34:35], off
	v_lshl_add_u64 v[34:35], s[28:29], 0, v[198:199]
	s_add_i32 m0, s4, 0xe000
	s_nop 0
	global_load_lds_dwordx4 v[34:35], off
	s_waitcnt vmcnt(8)
	s_waitcnt lgkmcnt(0)
	s_barrier
	s_setprio 1
	s_waitcnt lgkmcnt(0)
	v_mfma_f32_16x16x32_bf16 v[84:87], v[72:75], v[168:171], v[84:87]
	v_mfma_f32_16x16x32_bf16 v[84:87], v[76:79], v[172:175], v[84:87]
	v_mfma_f32_16x16x32_bf16 v[148:151], v[88:91], v[172:175], v[148:151]
	v_mfma_f32_16x16x32_bf16 v[148:151], v[80:83], v[168:171], v[148:151]
	v_mfma_f32_16x16x32_bf16 v[132:135], v[80:83], v[176:179], v[132:135]
	v_mfma_f32_16x16x32_bf16 v[132:135], v[88:91], v[186:189], v[132:135]
	v_mfma_f32_16x16x32_bf16 v[136:139], v[76:79], v[186:189], v[136:139]
	v_mfma_f32_16x16x32_bf16 v[136:139], v[72:75], v[176:179], v[136:139]
	v_mfma_f32_16x16x32_bf16 v[120:123], v[72:75], v[200:203], v[120:123]
	v_mfma_f32_16x16x32_bf16 v[120:123], v[76:79], v[204:207], v[120:123]
	v_mfma_f32_16x16x32_bf16 v[116:119], v[88:91], v[204:207], v[116:119]
	v_mfma_f32_16x16x32_bf16 v[116:119], v[80:83], v[200:203], v[116:119]
	v_mfma_f32_16x16x32_bf16 v[100:103], v[80:83], v[208:211], v[100:103]
	v_mfma_f32_16x16x32_bf16 v[100:103], v[88:91], v[212:215], v[100:103]
	v_mfma_f32_16x16x32_bf16 v[104:107], v[76:79], v[212:215], v[104:107]
	v_mfma_f32_16x16x32_bf16 v[104:107], v[72:75], v[208:211], v[104:107]
	s_setprio 0
	s_setprio 1
	v_mfma_f32_16x16x32_bf16 v[144:147], v[152:155], v[168:171], v[144:147]
	v_mfma_f32_16x16x32_bf16 v[144:147], v[156:159], v[172:175], v[144:147]
	v_mfma_f32_16x16x32_bf16 v[140:143], v[164:167], v[172:175], v[140:143]
	v_mfma_f32_16x16x32_bf16 v[140:143], v[160:163], v[168:171], v[140:143]
	v_mfma_f32_16x16x32_bf16 v[124:127], v[160:163], v[176:179], v[124:127]
	v_mfma_f32_16x16x32_bf16 v[124:127], v[164:167], v[186:189], v[124:127]
	v_mfma_f32_16x16x32_bf16 v[128:131], v[156:159], v[186:189], v[128:131]
	v_mfma_f32_16x16x32_bf16 v[128:131], v[152:155], v[176:179], v[128:131]
	v_mfma_f32_16x16x32_bf16 v[112:115], v[152:155], v[200:203], v[112:115]
	v_mfma_f32_16x16x32_bf16 v[112:115], v[156:159], v[204:207], v[112:115]
	v_mfma_f32_16x16x32_bf16 v[108:111], v[164:167], v[204:207], v[108:111]
	v_mfma_f32_16x16x32_bf16 v[108:111], v[160:163], v[200:203], v[108:111]
	v_mfma_f32_16x16x32_bf16 v[92:95], v[160:163], v[208:211], v[92:95]
	v_mfma_f32_16x16x32_bf16 v[92:95], v[164:167], v[212:215], v[92:95]
	v_mfma_f32_16x16x32_bf16 v[96:99], v[156:159], v[212:215], v[96:99]
	v_mfma_f32_16x16x32_bf16 v[96:99], v[152:155], v[208:211], v[96:99]
	s_setprio 0
	s_barrier
	s_add_i32 s27, s27, s3
	v_lshl_add_u64 v[190:191], s[38:39], 0, v[30:31]
	s_mov_b32 m0, s27
	ds_read_b128 v[168:171], v251 offset:16384
	ds_read_b128 v[172:175], v251 offset:17408
	ds_read_b128 v[176:179], v251 offset:18432
	ds_read_b128 v[186:189], v251 offset:19456
	ds_read_b128 v[200:203], v251 offset:20480
	ds_read_b128 v[204:207], v251 offset:21504
	ds_read_b128 v[208:211], v251 offset:22528
	ds_read_b128 v[212:215], v251 offset:23552
	global_load_lds_dwordx4 v[190:191], off
	s_add_i32 m0, s27, 0x2000
	s_add_u32 s28, s38, 0x200000
	v_lshl_add_u64 v[216:217], s[38:39], 0, v[180:181]
	s_addc_u32 s29, s39, 0
	s_add_i32 s27, s33, s3
	global_load_lds_dwordx4 v[216:217], off
	v_lshl_add_u64 v[34:35], s[28:29], 0, v[30:31]
	s_mov_b32 m0, s27
	v_lshl_add_u64 v[218:219], s[92:93], 0, v[30:31]
	global_load_lds_dwordx4 v[34:35], off
	v_lshl_add_u64 v[34:35], s[28:29], 0, v[180:181]
	s_add_i32 m0, s27, 0x2000
	v_lshl_add_u64 v[220:221], s[92:93], 0, v[180:181]
	global_load_lds_dwordx4 v[34:35], off
	s_mov_b32 m0, s4
	s_nop 0
	global_load_lds_dwordx4 v[218:219], off
	s_mov_b32 m0, s5
	s_nop 0
	global_load_lds_dwordx4 v[220:221], off
	s_waitcnt vmcnt(8)
	s_waitcnt lgkmcnt(0)
	s_barrier
; #define PG8_STAGE(bufoff, gbase, voff) do { _Pragma("unroll") for (int _i = 0; _i < 2; ++_i) \
;         __builtin_amdgcn_global_load_lds((const unsigned*)((const char*)(gbase) + (voff)[_i]), (PG8_LAS unsigned*)(lds + (bufoff) + ldsw + _i * 8192), 16, 0, 0); } while (0)
; #define PG8_LDA(dst, b, h) do { _Pragma("unroll") for (int m = 0; m < 4; ++m) _Pragma("unroll") for (int k = 0; k < 2; ++k) dst[m][k] = *(const PG8_LAS bf16x8*)(lds + PG8_SA(b, h) + aoff + m * 2048 + k * 1024); } while (0)
; #define PG8_LDB(dst, b, h) do { _Pragma("unroll") for (int n = 0; n < 2; ++n) _Pragma("unroll") for (int k = 0; k < 2; ++k) dst[n][k] = *(const PG8_LAS bf16x8*)(lds + PG8_SB(b, h) + boff + n * 2048 + k * 1024); } while (0)
; #define PG8_MMA(ai, bj, At, Bt) do { __builtin_amdgcn_s_setprio(1); _Pragma("unroll") for (int m = 0; m < 4; ++m) _Pragma("unroll") for (int n = 0; n < 2; ++n) _Pragma("unroll") for (int k = 0; k < 2; ++k) \
;         acc[ai][bj][m][n] = __builtin_amdgcn_mfma_f32_16x16x32_bf16(Bt[n][k], At[m][k], acc[ai][bj][m][n], 0, 0, 0); __builtin_amdgcn_s_setprio(0); } while (0)
; #define PG8_WAIT_V(n) asm volatile("s_waitcnt vmcnt(" #n ")" ::: "memory")
; #define PG8_WAIT_L(n) asm volatile("s_waitcnt lgkmcnt(" #n ")" ::: "memory")
; #define PG8_BAR __builtin_amdgcn_s_barrier()
; #define PG8_SCHED __builtin_amdgcn_sched_barrier(0)
;     ...
;             PG8_WAIT_V(8); PG8_WAIT_L(0); PG8_BAR; PG8_MMA(1, 0, At, B0); PG8_MMA(1, 1, At, B1); PG8_BAR; PG8_SCHED;
;             PG8_LDB(B0, 1, 0); PG8_LDB(B1, 1, 1); PG8_SCHED; PG8_LDA(At, 1, 0); PG8_STAGE(PG8_SA(0, 1), a2 + hstepA, voffA);
;             PG8_WAIT_V(8); PG8_WAIT_L(0); PG8_BAR; PG8_MMA(0, 0, At, B0); PG8_MMA(0, 1, At, B1); PG8_BAR; PG8_SCHED;
	s_setprio 1
	s_waitcnt lgkmcnt(0)
	v_mfma_f32_16x16x32_bf16 v[68:71], v[72:75], v[168:171], v[68:71]
	v_mfma_f32_16x16x32_bf16 v[68:71], v[76:79], v[172:175], v[68:71]
	v_mfma_f32_16x16x32_bf16 v[64:67], v[88:91], v[172:175], v[64:67]
	v_mfma_f32_16x16x32_bf16 v[64:67], v[80:83], v[168:171], v[64:67]
	v_mfma_f32_16x16x32_bf16 v[48:51], v[80:83], v[176:179], v[48:51]
	v_mfma_f32_16x16x32_bf16 v[48:51], v[88:91], v[186:189], v[48:51]
	v_mfma_f32_16x16x32_bf16 v[52:55], v[76:79], v[186:189], v[52:55]
	v_mfma_f32_16x16x32_bf16 v[52:55], v[72:75], v[176:179], v[52:55]
	v_mfma_f32_16x16x32_bf16 v[34:37], v[72:75], v[200:203], v[36:39]
	v_mfma_f32_16x16x32_bf16 v[34:37], v[76:79], v[204:207], v[34:37]
	v_mfma_f32_16x16x32_bf16 v[26:29], v[88:91], v[204:207], v[26:29]
	v_mfma_f32_16x16x32_bf16 v[26:29], v[80:83], v[200:203], v[26:29]
	v_mfma_f32_16x16x32_bf16 v[10:13], v[80:83], v[208:211], v[10:13]
	v_mfma_f32_16x16x32_bf16 v[10:13], v[88:91], v[212:215], v[10:13]
	v_mfma_f32_16x16x32_bf16 v[14:17], v[76:79], v[212:215], v[14:17]
	v_mfma_f32_16x16x32_bf16 v[14:17], v[72:75], v[208:211], v[14:17]
	s_setprio 0
	s_setprio 1
	v_mfma_f32_16x16x32_bf16 v[60:63], v[152:155], v[168:171], v[60:63]
	v_mfma_f32_16x16x32_bf16 v[60:63], v[156:159], v[172:175], v[60:63]
	v_mfma_f32_16x16x32_bf16 v[56:59], v[164:167], v[172:175], v[56:59]
	v_mfma_f32_16x16x32_bf16 v[56:59], v[160:163], v[168:171], v[56:59]
	v_mfma_f32_16x16x32_bf16 v[38:41], v[160:163], v[176:179], v[40:43]
	v_mfma_f32_16x16x32_bf16 v[40:43], v[164:167], v[186:189], v[38:41]
	v_mfma_f32_16x16x32_bf16 v[44:47], v[156:159], v[186:189], v[44:47]
	v_mfma_f32_16x16x32_bf16 v[44:47], v[152:155], v[176:179], v[44:47]
	v_mfma_f32_16x16x32_bf16 v[22:25], v[152:155], v[200:203], v[22:25]
	v_mfma_f32_16x16x32_bf16 v[22:25], v[156:159], v[204:207], v[22:25]
	v_mfma_f32_16x16x32_bf16 v[18:21], v[164:167], v[204:207], v[18:21]
	v_mfma_f32_16x16x32_bf16 v[18:21], v[160:163], v[200:203], v[18:21]
	v_mfma_f32_16x16x32_bf16 v[2:5], v[160:163], v[208:211], v[2:5]
	v_mfma_f32_16x16x32_bf16 v[2:5], v[164:167], v[212:215], v[2:5]
	v_mfma_f32_16x16x32_bf16 v[6:9], v[156:159], v[212:215], v[6:9]
	v_mfma_f32_16x16x32_bf16 v[6:9], v[152:155], v[208:211], v[6:9]
	s_setprio 0
	s_barrier
	s_add_i32 s27, 0, 0x18000
	v_add_u32_e32 v32, s27, v239
	s_add_i32 s33, 0, 0x1c000
	ds_read_b128 v[72:75], v32
	ds_read_b128 v[76:79], v32 offset:1024
	ds_read_b128 v[80:83], v32 offset:2048
	ds_read_b128 v[88:91], v32 offset:3072
	v_add_u32_e32 v32, s33, v239
	ds_read_b128 v[152:155], v32
	ds_read_b128 v[156:159], v32 offset:1024
	ds_read_b128 v[160:163], v32 offset:2048
	ds_read_b128 v[164:167], v32 offset:3072
	s_add_u32 s28, s92, 0x200000
	s_addc_u32 s29, s93, 0
	s_mov_b32 m0, s42
	v_lshl_add_u64 v[38:39], s[28:29], 0, v[30:31]
	ds_read_b128 v[168:171], v251 offset:32768
	ds_read_b128 v[172:175], v251 offset:33792
	ds_read_b128 v[176:179], v251 offset:34816
	ds_read_b128 v[186:189], v251 offset:35840
	ds_read_b128 v[200:203], v251 offset:36864
	ds_read_b128 v[204:207], v251 offset:37888
	ds_read_b128 v[208:211], v251 offset:38912
	ds_read_b128 v[212:215], v251 offset:39936
	global_load_lds_dwordx4 v[38:39], off
	v_lshl_add_u64 v[38:39], s[28:29], 0, v[180:181]
	s_mov_b32 m0, s41
	s_nop 0
	global_load_lds_dwordx4 v[38:39], off
	s_waitcnt vmcnt(8)
	s_waitcnt lgkmcnt(0)
	s_barrier
	s_setprio 1
	s_waitcnt lgkmcnt(0)
	v_mfma_f32_16x16x32_bf16 v[84:87], v[72:75], v[168:171], v[84:87]
	v_mfma_f32_16x16x32_bf16 v[84:87], v[76:79], v[172:175], v[84:87]
	v_mfma_f32_16x16x32_bf16 v[148:151], v[88:91], v[172:175], v[148:151]
	v_mfma_f32_16x16x32_bf16 v[148:151], v[80:83], v[168:171], v[148:151]
	v_mfma_f32_16x16x32_bf16 v[132:135], v[80:83], v[176:179], v[132:135]
	v_mfma_f32_16x16x32_bf16 v[132:135], v[88:91], v[186:189], v[132:135]
	v_mfma_f32_16x16x32_bf16 v[136:139], v[76:79], v[186:189], v[136:139]
	v_mfma_f32_16x16x32_bf16 v[136:139], v[72:75], v[176:179], v[136:139]
	v_mfma_f32_16x16x32_bf16 v[120:123], v[72:75], v[200:203], v[120:123]
	v_mfma_f32_16x16x32_bf16 v[120:123], v[76:79], v[204:207], v[120:123]
	v_mfma_f32_16x16x32_bf16 v[116:119], v[88:91], v[204:207], v[116:119]
	v_mfma_f32_16x16x32_bf16 v[116:119], v[80:83], v[200:203], v[116:119]
	v_mfma_f32_16x16x32_bf16 v[100:103], v[80:83], v[208:211], v[100:103]
	v_mfma_f32_16x16x32_bf16 v[100:103], v[88:91], v[212:215], v[100:103]
	v_mfma_f32_16x16x32_bf16 v[104:107], v[76:79], v[212:215], v[104:107]
	v_mfma_f32_16x16x32_bf16 v[104:107], v[72:75], v[208:211], v[104:107]
	s_setprio 0
	s_setprio 1
	v_mfma_f32_16x16x32_bf16 v[144:147], v[152:155], v[168:171], v[144:147]
	v_mfma_f32_16x16x32_bf16 v[144:147], v[156:159], v[172:175], v[144:147]
	v_mfma_f32_16x16x32_bf16 v[140:143], v[164:167], v[172:175], v[140:143]
	v_mfma_f32_16x16x32_bf16 v[140:143], v[160:163], v[168:171], v[140:143]
	v_mfma_f32_16x16x32_bf16 v[124:127], v[160:163], v[176:179], v[124:127]
	v_mfma_f32_16x16x32_bf16 v[124:127], v[164:167], v[186:189], v[124:127]
	v_mfma_f32_16x16x32_bf16 v[128:131], v[156:159], v[186:189], v[128:131]
	v_mfma_f32_16x16x32_bf16 v[128:131], v[152:155], v[176:179], v[128:131]
	v_mfma_f32_16x16x32_bf16 v[112:115], v[152:155], v[200:203], v[112:115]
	v_mfma_f32_16x16x32_bf16 v[112:115], v[156:159], v[204:207], v[112:115]
	v_mfma_f32_16x16x32_bf16 v[108:111], v[164:167], v[204:207], v[108:111]
	v_mfma_f32_16x16x32_bf16 v[108:111], v[160:163], v[200:203], v[108:111]
	v_mfma_f32_16x16x32_bf16 v[92:95], v[160:163], v[208:211], v[92:95]
	v_mfma_f32_16x16x32_bf16 v[92:95], v[164:167], v[212:215], v[92:95]
	v_mfma_f32_16x16x32_bf16 v[96:99], v[156:159], v[212:215], v[96:99]
	v_mfma_f32_16x16x32_bf16 v[96:99], v[152:155], v[208:211], v[96:99]
	s_setprio 0
	s_barrier
; #define PG8_STAGE(bufoff, gbase, voff) do { _Pragma("unroll") for (int _i = 0; _i < 2; ++_i) \
;         __builtin_amdgcn_global_load_lds((const unsigned*)((const char*)(gbase) + (voff)[_i]), (PG8_LAS unsigned*)(lds + (bufoff) + ldsw + _i * 8192), 16, 0, 0); } while (0)
; #define PG8_LDA(dst, b, h) do { _Pragma("unroll") for (int m = 0; m < 4; ++m) _Pragma("unroll") for (int k = 0; k < 2; ++k) dst[m][k] = *(const PG8_LAS bf16x8*)(lds + PG8_SA(b, h) + aoff + m * 2048 + k * 1024); } while (0)
; #define PG8_MMA(ai, bj, At, Bt) do { __builtin_amdgcn_s_setprio(1); _Pragma("unroll") for (int m = 0; m < 4; ++m) _Pragma("unroll") for (int n = 0; n < 2; ++n) _Pragma("unroll") for (int k = 0; k < 2; ++k) \
;         acc[ai][bj][m][n] = __builtin_amdgcn_mfma_f32_16x16x32_bf16(Bt[n][k], At[m][k], acc[ai][bj][m][n], 0, 0, 0); __builtin_amdgcn_s_setprio(0); } while (0)
; #define PG8_WAIT_V(n) asm volatile("s_waitcnt vmcnt(" #n ")" ::: "memory")
; #define PG8_WAIT_L(n) asm volatile("s_waitcnt lgkmcnt(" #n ")" ::: "memory")
; #define PG8_BAR __builtin_amdgcn_s_barrier()
; #define PG8_SCHED __builtin_amdgcn_sched_barrier(0)
;     ...
;             PG8_LDA(At, 1, 1); PG8_STAGE(PG8_SB(1, 0), b3, voffB); PG8_STAGE(PG8_SB(1, 1), b3 + hstep, voffB); PG8_STAGE(PG8_SA(1, 0), a3, voffA);
;             PG8_WAIT_V(8); PG8_WAIT_L(0); PG8_BAR; PG8_MMA(1, 0, At, B0); PG8_MMA(1, 1, At, B1); PG8_BAR; PG8_SCHED;
;     ...
;         if constexpr (ALIGN_EPI) { if (wr == 0) PG8_BAR; }
	s_add_i32 s27, s27, s3
	v_lshl_add_u64 v[38:39], v[190:191], 0, s[64:65]
	s_mov_b32 m0, s27
	ds_read_b128 v[168:171], v251 offset:49152
	ds_read_b128 v[172:175], v251 offset:50176
	ds_read_b128 v[176:179], v251 offset:51200
	ds_read_b128 v[186:189], v251 offset:52224
	ds_read_b128 v[200:203], v251 offset:53248
	ds_read_b128 v[204:207], v251 offset:54272
	ds_read_b128 v[208:211], v251 offset:55296
	ds_read_b128 v[212:215], v251 offset:56320
	global_load_lds_dwordx4 v[38:39], off
	s_add_i32 m0, s27, 0x2000
	s_add_u32 s28, s38, 0x200080
	v_lshl_add_u64 v[38:39], v[216:217], 0, s[64:65]
	s_addc_u32 s29, s39, 0
	s_add_i32 s27, s33, s3
	global_load_lds_dwordx4 v[38:39], off
	v_lshl_add_u64 v[38:39], s[28:29], 0, v[30:31]
	s_mov_b32 m0, s27
	s_nop 0
	global_load_lds_dwordx4 v[38:39], off
	v_lshl_add_u64 v[38:39], s[28:29], 0, v[180:181]
	s_add_i32 m0, s27, 0x2000
	s_nop 0
	global_load_lds_dwordx4 v[38:39], off
	v_lshl_add_u64 v[38:39], v[218:219], 0, s[64:65]
	s_mov_b32 m0, s53
	s_nop 0
	global_load_lds_dwordx4 v[38:39], off
	v_lshl_add_u64 v[38:39], v[220:221], 0, s[64:65]
	s_mov_b32 m0, s10
	s_nop 0
	global_load_lds_dwordx4 v[38:39], off
	s_waitcnt vmcnt(8)
	s_waitcnt lgkmcnt(0)
	s_barrier
	s_setprio 1
	s_waitcnt lgkmcnt(0)
	v_mfma_f32_16x16x32_bf16 v[68:71], v[72:75], v[168:171], v[68:71]
	v_mfma_f32_16x16x32_bf16 v[68:71], v[76:79], v[172:175], v[68:71]
	v_mfma_f32_16x16x32_bf16 v[64:67], v[88:91], v[172:175], v[64:67]
	v_mfma_f32_16x16x32_bf16 v[64:67], v[80:83], v[168:171], v[64:67]
	v_mfma_f32_16x16x32_bf16 v[48:51], v[80:83], v[176:179], v[48:51]
	v_mfma_f32_16x16x32_bf16 v[48:51], v[88:91], v[186:189], v[48:51]
	v_mfma_f32_16x16x32_bf16 v[52:55], v[76:79], v[186:189], v[52:55]
	v_mfma_f32_16x16x32_bf16 v[52:55], v[72:75], v[176:179], v[52:55]
	v_mfma_f32_16x16x32_bf16 v[34:37], v[72:75], v[200:203], v[34:37]
	v_mfma_f32_16x16x32_bf16 v[36:39], v[76:79], v[204:207], v[34:37]
	v_mfma_f32_16x16x32_bf16 v[26:29], v[88:91], v[204:207], v[26:29]
	v_mfma_f32_16x16x32_bf16 v[26:29], v[80:83], v[200:203], v[26:29]
	v_mfma_f32_16x16x32_bf16 v[10:13], v[80:83], v[208:211], v[10:13]
	v_mfma_f32_16x16x32_bf16 v[10:13], v[88:91], v[212:215], v[10:13]
	v_mfma_f32_16x16x32_bf16 v[14:17], v[76:79], v[212:215], v[14:17]
	v_mfma_f32_16x16x32_bf16 v[14:17], v[72:75], v[208:211], v[14:17]
	s_setprio 0
	s_setprio 1
	v_mfma_f32_16x16x32_bf16 v[60:63], v[152:155], v[168:171], v[60:63]
	v_mfma_f32_16x16x32_bf16 v[60:63], v[156:159], v[172:175], v[60:63]
	v_mfma_f32_16x16x32_bf16 v[56:59], v[164:167], v[172:175], v[56:59]
	v_mfma_f32_16x16x32_bf16 v[56:59], v[160:163], v[168:171], v[56:59]
	v_mfma_f32_16x16x32_bf16 v[40:43], v[160:163], v[176:179], v[40:43]
	v_mfma_f32_16x16x32_bf16 v[40:43], v[164:167], v[186:189], v[40:43]
	v_mfma_f32_16x16x32_bf16 v[44:47], v[156:159], v[186:189], v[44:47]
	v_mfma_f32_16x16x32_bf16 v[44:47], v[152:155], v[176:179], v[44:47]
	v_mfma_f32_16x16x32_bf16 v[22:25], v[152:155], v[200:203], v[22:25]
	v_mfma_f32_16x16x32_bf16 v[22:25], v[156:159], v[204:207], v[22:25]
	v_mfma_f32_16x16x32_bf16 v[18:21], v[164:167], v[204:207], v[18:21]
	v_mfma_f32_16x16x32_bf16 v[18:21], v[160:163], v[200:203], v[18:21]
	v_mfma_f32_16x16x32_bf16 v[2:5], v[160:163], v[208:211], v[2:5]
	v_mfma_f32_16x16x32_bf16 v[2:5], v[164:167], v[212:215], v[2:5]
	v_mfma_f32_16x16x32_bf16 v[6:9], v[156:159], v[212:215], v[6:9]
	v_mfma_f32_16x16x32_bf16 v[6:9], v[152:155], v[208:211], v[6:9]
	s_setprio 0
	s_barrier
	s_add_i32 s27, s25, 2
	s_add_u32 s9, s9, 0x100
	s_addc_u32 s23, s23, 0
	s_cmp_ge_i32 s25, s40
	s_mov_b64 s[28:29], s[30:31]
	s_mov_b32 s25, s27
	s_cbranch_scc0 .LBB0_1454
	s_and_b64 vcc, exec, s[16:17]
	s_cbranch_vccz .LBB0_1457
	s_barrier
